# out-proj and FFN-out GEMMs on a hand-pipelined k-loop with a 4-slot LDS ring (three k-tiles of LDS-DMA in flight, static LDS 81920 B, barrier state saved/restored)
# speedup vs baseline: 1.0150x; 1.0150x over previous
.LBB0_52:
	s_ashr_i32 s0, s5, 31
	s_lshr_b32 s0, s0, 27
	s_add_i32 s0, s5, s0
	s_and_b32 s1, s0, 0xffffffe0
	s_sub_i32 s7, s5, s1
	s_lshl_b32 s0, s0, 2
	s_and_b32 s6, s0, 0xffffff80
	s_mul_i32 s0, s7, 0x84000
	s_ashr_i32 s1, s0, 31
	s_lshl_b64 s[0:1], s[0:1], 1
	v_lshl_add_u64 v[0:1], v[98:99], 0, s[0:1]
	v_readfirstlane_b32 s8, v142
	v_lshl_add_u64 v[4:5], v[0:1], 0, v[112:113]
	s_mov_b32 m0, s8
	v_readfirstlane_b32 s8, v143
	global_load_lds_dwordx4 v[4:5], off
	v_lshl_add_u64 v[6:7], v[0:1], 0, v[114:115]
	s_mov_b32 m0, s8
	v_readfirstlane_b32 s8, v144
	v_add_u32_e32 v10, 0x3000, v142
	v_mad_i64_i32 v[2:3], s[10:11], s6, v188, v[100:101]
	global_load_lds_dwordx4 v[6:7], off
	v_lshl_add_u64 v[0:1], v[0:1], 0, v[96:97]
	s_mov_b32 m0, s8
	v_readfirstlane_b32 s8, v10
	v_add_u32_e32 v10, 0x4000, v142
	global_load_lds_dwordx4 v[0:1], off
	v_lshl_add_u64 v[8:9], v[2:3], 0, v[112:113]
	s_mov_b32 m0, s8
	v_readfirstlane_b32 s8, v10
	v_add_u32_e32 v10, 0x5000, v142
	global_load_lds_dwordx4 v[8:9], off
	v_lshl_add_u64 v[2:3], v[2:3], 0, v[114:115]
	s_mov_b32 m0, s8
	v_readfirstlane_b32 s8, v10
	global_load_lds_dwordx4 v[2:3], off
	v_lshl_add_u64 v[4:5], v[4:5], 0, 64
	s_mov_b32 m0, s8
	v_lshl_add_u64 v[0:1], v[0:1], 0, 64
	global_load_lds_dwordx4 v[4:5], off
	v_lshl_add_u64 v[4:5], v[6:7], 0, 64
	v_add_u32_e32 v6, 0x6000, v142
	s_mov_b32 s9, 2
	v_readfirstlane_b32 s8, v6
	s_mov_b32 m0, s8
	v_mad_i64_i32 v[116:117], s[10:11], s6, v188, v[102:103]
	global_load_lds_dwordx4 v[4:5], off
	v_add_u32_e32 v4, 0x7000, v142
	v_mad_i64_i32 v[118:119], s[10:11], s6, v188, v[104:105]
	v_readfirstlane_b32 s8, v4
	v_add_u32_e32 v4, 0x8000, v142
	s_mov_b32 m0, s8
	v_readfirstlane_b32 s8, v4
	global_load_lds_dwordx4 v[0:1], off
	v_lshl_add_u64 v[0:1], v[8:9], 0, 64
	s_mov_b32 m0, s8
	v_lshl_add_u64 v[120:121], v[106:107], 0, s[0:1]
	global_load_lds_dwordx4 v[0:1], off
	v_lshl_add_u64 v[0:1], v[2:3], 0, 64
	v_add_u32_e32 v2, 0x9000, v142
	v_lshl_add_u64 v[122:123], v[108:109], 0, s[0:1]
	v_readfirstlane_b32 s8, v2
	s_mov_b32 m0, s8
	v_lshl_add_u64 v[124:125], v[110:111], 0, s[0:1]
	global_load_lds_dwordx4 v[0:1], off
	v_mov_b32_e32 v0, 0
	s_mov_b32 s8, 0
	s_mov_b64 s[0:1], 0
	v_mov_b32_e32 v1, v0
	v_mov_b32_e32 v2, v0
	v_mov_b32_e32 v3, v0
	v_mov_b32_e32 v12, v0
	v_mov_b32_e32 v13, v0
	v_mov_b32_e32 v14, v0
	v_mov_b32_e32 v15, v0
	v_mov_b32_e32 v4, v0
	v_mov_b32_e32 v5, v0
	v_mov_b32_e32 v6, v0
	v_mov_b32_e32 v7, v0
	v_mov_b32_e32 v8, v0
	v_mov_b32_e32 v9, v0
	v_mov_b32_e32 v10, v0
	v_mov_b32_e32 v11, v0
	v_mov_b32_e32 v16, v0
	v_mov_b32_e32 v17, v0
	v_mov_b32_e32 v18, v0
	v_mov_b32_e32 v19, v0
	v_mov_b32_e32 v20, v0
	v_mov_b32_e32 v21, v0
	v_mov_b32_e32 v22, v0
	v_mov_b32_e32 v23, v0
	v_mov_b32_e32 v24, v0
	v_mov_b32_e32 v25, v0
	v_mov_b32_e32 v26, v0
	v_mov_b32_e32 v27, v0
	v_mov_b32_e32 v28, v0
	v_mov_b32_e32 v29, v0
	v_mov_b32_e32 v30, v0
	v_mov_b32_e32 v31, v0
	v_mov_b32_e32 v32, v0
	v_mov_b32_e32 v33, v0
	v_mov_b32_e32 v34, v0
	v_mov_b32_e32 v35, v0
	v_mov_b32_e32 v36, v0
	v_mov_b32_e32 v37, v0
	v_mov_b32_e32 v38, v0
	v_mov_b32_e32 v39, v0
	v_mov_b32_e32 v40, v0
	v_mov_b32_e32 v41, v0
	v_mov_b32_e32 v42, v0
	v_mov_b32_e32 v43, v0
	v_mov_b32_e32 v44, v0
	v_mov_b32_e32 v45, v0
	v_mov_b32_e32 v46, v0
	v_mov_b32_e32 v47, v0
	v_mov_b32_e32 v48, v0
	v_mov_b32_e32 v49, v0
	v_mov_b32_e32 v50, v0
	v_mov_b32_e32 v51, v0
	v_mov_b32_e32 v52, v0
	v_mov_b32_e32 v53, v0
	v_mov_b32_e32 v54, v0
	v_mov_b32_e32 v55, v0
	v_mov_b32_e32 v56, v0
	v_mov_b32_e32 v57, v0
	v_mov_b32_e32 v58, v0
	v_mov_b32_e32 v59, v0
	v_mov_b32_e32 v60, v0
	v_mov_b32_e32 v61, v0
	v_mov_b32_e32 v62, v0
	v_mov_b32_e32 v63, v0
	v_mov_b32_e32 v64, v0
	v_mov_b32_e32 v65, v0
	v_mov_b32_e32 v66, v0
	v_mov_b32_e32 v67, v0
	v_mov_b32_e32 v68, v0
	v_mov_b32_e32 v69, v0
	v_mov_b32_e32 v70, v0
	v_mov_b32_e32 v71, v0
	v_mov_b32_e32 v72, v0
	v_mov_b32_e32 v73, v0
	v_mov_b32_e32 v74, v0
	v_mov_b32_e32 v75, v0
	v_mov_b32_e32 v76, v0
	v_mov_b32_e32 v77, v0
	v_mov_b32_e32 v78, v0
	v_mov_b32_e32 v79, v0
	v_mov_b32_e32 v80, v0
	v_mov_b32_e32 v81, v0
	v_mov_b32_e32 v82, v0
	v_mov_b32_e32 v83, v0
	v_mov_b32_e32 v84, v0
	v_mov_b32_e32 v85, v0
	v_mov_b32_e32 v86, v0
	v_mov_b32_e32 v87, v0
	v_mov_b32_e32 v88, v0
	v_mov_b32_e32 v89, v0
	v_mov_b32_e32 v90, v0
	v_mov_b32_e32 v91, v0
	v_mov_b32_e32 v92, v0
	v_mov_b32_e32 v93, v0
	v_mov_b32_e32 v94, v0
	v_mov_b32_e32 v95, v0
	v_readfirstlane_b32 s34, v142
	s_mov_b32 s36, 0x5000
	s_mov_b32 s37, 0xffff1000
	ds_read_b32 v252, v183
	ds_read_b32 v253, v184
	s_waitcnt lgkmcnt(0)
	v_readfirstlane_b32 s46, v252
	v_readfirstlane_b32 s47, v253
	s_barrier
	s_add_u32 s39, s34, 0xa000
	v_lshl_add_u64 v[126:127], v[124:125], 0, s[2:3]
	s_mov_b32 m0, s39
	s_nop 0
	global_load_lds_dwordx4 v[126:127], off
	v_lshl_add_u64 v[126:127], v[122:123], 0, s[2:3]
	s_add_u32 m0, s39, 0x1000
	s_nop 0
	global_load_lds_dwordx4 v[126:127], off
	v_lshl_add_u64 v[126:127], v[120:121], 0, s[2:3]
	s_add_u32 m0, s39, 0x2000
	s_nop 0
	global_load_lds_dwordx4 v[126:127], off
	v_lshl_add_u64 v[126:127], v[118:119], 0, s[2:3]
	s_add_u32 m0, s39, 0x3000
	s_nop 0
	global_load_lds_dwordx4 v[126:127], off
	v_lshl_add_u64 v[126:127], v[116:117], 0, s[2:3]
	s_add_u32 m0, s39, 0x4000
	s_nop 0
	global_load_lds_dwordx4 v[126:127], off
	s_add_u32 s39, s34, 0xf000
	v_lshl_add_u64 v[126:127], v[124:125], 0, s[30:31]
	s_mov_b32 m0, s39
	s_nop 0
	global_load_lds_dwordx4 v[126:127], off
	v_lshl_add_u64 v[126:127], v[122:123], 0, s[30:31]
	s_add_u32 m0, s39, 0x1000
	s_nop 0
	global_load_lds_dwordx4 v[126:127], off
	v_lshl_add_u64 v[126:127], v[120:121], 0, s[30:31]
	s_add_u32 m0, s39, 0x2000
	s_nop 0
	global_load_lds_dwordx4 v[126:127], off
	v_lshl_add_u64 v[126:127], v[118:119], 0, s[30:31]
	s_add_u32 m0, s39, 0x3000
	s_nop 0
	global_load_lds_dwordx4 v[126:127], off
	v_lshl_add_u64 v[126:127], v[116:117], 0, s[30:31]
	s_add_u32 m0, s39, 0x4000
	s_nop 0
	global_load_lds_dwordx4 v[126:127], off
	s_mov_b64 s[42:43], 0x100
	v_lshl_add_u64 v[124:125], v[124:125], 0, s[42:43]
	v_lshl_add_u64 v[122:123], v[122:123], 0, s[42:43]
	v_lshl_add_u64 v[120:121], v[120:121], 0, s[42:43]
	v_lshl_add_u64 v[236:237], v[118:119], 0, s[42:43]
	v_lshl_add_u64 v[126:127], v[116:117], 0, s[42:43]
	v_add_u32_e32 v170, v147, v128
	v_add_u32_e32 v172, v149, v148
	s_mov_b32 s35, 0
	s_mov_b32 s41, 42
	s_waitcnt vmcnt(15)
	s_barrier
	ds_read_b128 v[134:137], v170
	ds_read_b128 v[138:141], v170 offset:1024
	ds_read_b128 v[150:153], v170 offset:2048
	ds_read_b128 v[154:157], v170 offset:3072
	ds_read_b128 v[158:161], v170 offset:4096
	ds_read_b128 v[162:165], v170 offset:5120
	ds_read_b128 v[166:169], v172 offset:12288
	ds_read_b128 v[200:203], v172 offset:13312
	ds_read_b128 v[204:207], v172 offset:14336
	ds_read_b128 v[208:211], v172 offset:15360
.Lk_ffo:
	s_waitcnt lgkmcnt(0)
	v_mfma_f32_16x16x32_bf16 v[92:95], v[166:169], v[134:137], v[92:95]
	s_waitcnt vmcnt(10)
	s_barrier
	v_mfma_f32_16x16x32_bf16 v[88:91], v[200:203], v[134:137], v[88:91]
	s_cmp_eq_u32 s35, 0xf000
	s_cselect_b32 s38, s37, s36
	s_add_u32 s39, s34, s35
	v_mfma_f32_16x16x32_bf16 v[84:87], v[204:207], v[134:137], v[84:87]
	v_add_u32_e32 v170, s38, v170
	v_add_u32_e32 v172, s38, v172
	s_add_u32 s35, s35, s38
	v_mfma_f32_16x16x32_bf16 v[80:83], v[208:211], v[134:137], v[80:83]
	ds_read_b128 v[212:215], v170
	v_mfma_f32_16x16x32_bf16 v[76:79], v[166:169], v[138:141], v[76:79]
	ds_read_b128 v[216:219], v170 offset:1024
	v_mfma_f32_16x16x32_bf16 v[72:75], v[200:203], v[138:141], v[72:75]
	ds_read_b128 v[220:223], v170 offset:2048
	v_mfma_f32_16x16x32_bf16 v[68:71], v[204:207], v[138:141], v[68:71]
	ds_read_b128 v[224:227], v170 offset:3072
	v_mfma_f32_16x16x32_bf16 v[64:67], v[208:211], v[138:141], v[64:67]
	ds_read_b128 v[228:231], v170 offset:4096
	v_mfma_f32_16x16x32_bf16 v[60:63], v[166:169], v[150:153], v[60:63]
	ds_read_b128 v[232:235], v170 offset:5120
	v_mfma_f32_16x16x32_bf16 v[56:59], v[200:203], v[150:153], v[56:59]
	ds_read_b128 v[244:247], v172 offset:12288
	v_mfma_f32_16x16x32_bf16 v[52:55], v[204:207], v[150:153], v[52:55]
	ds_read_b128 v[248:251], v172 offset:13312
	v_mfma_f32_16x16x32_bf16 v[48:51], v[208:211], v[150:153], v[48:51]
	ds_read_b128 v[252:255], v172 offset:14336
	v_mfma_f32_16x16x32_bf16 v[44:47], v[166:169], v[154:157], v[44:47]
	ds_read_b128 v[116:119], v172 offset:15360
	v_mfma_f32_16x16x32_bf16 v[40:43], v[200:203], v[154:157], v[40:43]
	s_mov_b32 m0, s39
	v_mfma_f32_16x16x32_bf16 v[36:39], v[204:207], v[154:157], v[36:39]
	global_load_lds_dwordx4 v[124:125], off
	v_lshl_add_u64 v[124:125], v[124:125], 0, 64
	v_mfma_f32_16x16x32_bf16 v[32:35], v[208:211], v[154:157], v[32:35]
	s_add_u32 m0, s39, 0x1000
	v_mfma_f32_16x16x32_bf16 v[28:31], v[166:169], v[158:161], v[28:31]
	global_load_lds_dwordx4 v[122:123], off
	v_lshl_add_u64 v[122:123], v[122:123], 0, 64
	v_mfma_f32_16x16x32_bf16 v[24:27], v[200:203], v[158:161], v[24:27]
	s_add_u32 m0, s39, 0x2000
	v_mfma_f32_16x16x32_bf16 v[20:23], v[204:207], v[158:161], v[20:23]
	global_load_lds_dwordx4 v[120:121], off
	v_lshl_add_u64 v[120:121], v[120:121], 0, 64
	v_mfma_f32_16x16x32_bf16 v[16:19], v[208:211], v[158:161], v[16:19]
	s_add_u32 m0, s39, 0x3000
	v_mfma_f32_16x16x32_bf16 v[8:11], v[166:169], v[162:165], v[8:11]
	global_load_lds_dwordx4 v[236:237], off
	v_lshl_add_u64 v[236:237], v[236:237], 0, 64
	v_mfma_f32_16x16x32_bf16 v[4:7], v[200:203], v[162:165], v[4:7]
	s_add_u32 m0, s39, 0x4000
	v_mfma_f32_16x16x32_bf16 v[12:15], v[204:207], v[162:165], v[12:15]
	global_load_lds_dwordx4 v[126:127], off
	v_lshl_add_u64 v[126:127], v[126:127], 0, 64
	v_mfma_f32_16x16x32_bf16 v[0:3], v[208:211], v[162:165], v[0:3]
	s_waitcnt lgkmcnt(0)
	v_mfma_f32_16x16x32_bf16 v[92:95], v[244:247], v[212:215], v[92:95]
	s_waitcnt vmcnt(10)
	s_barrier
	v_mfma_f32_16x16x32_bf16 v[88:91], v[248:251], v[212:215], v[88:91]
	s_cmp_eq_u32 s35, 0xf000
	s_cselect_b32 s38, s37, s36
	s_add_u32 s39, s34, s35
	v_mfma_f32_16x16x32_bf16 v[84:87], v[252:255], v[212:215], v[84:87]
	v_add_u32_e32 v170, s38, v170
	v_add_u32_e32 v172, s38, v172
	s_add_u32 s35, s35, s38
	v_mfma_f32_16x16x32_bf16 v[80:83], v[116:119], v[212:215], v[80:83]
	ds_read_b128 v[134:137], v170
	v_mfma_f32_16x16x32_bf16 v[76:79], v[244:247], v[216:219], v[76:79]
	ds_read_b128 v[138:141], v170 offset:1024
	v_mfma_f32_16x16x32_bf16 v[72:75], v[248:251], v[216:219], v[72:75]
	ds_read_b128 v[150:153], v170 offset:2048
	v_mfma_f32_16x16x32_bf16 v[68:71], v[252:255], v[216:219], v[68:71]
	ds_read_b128 v[154:157], v170 offset:3072
	v_mfma_f32_16x16x32_bf16 v[64:67], v[116:119], v[216:219], v[64:67]
	ds_read_b128 v[158:161], v170 offset:4096
	v_mfma_f32_16x16x32_bf16 v[60:63], v[244:247], v[220:223], v[60:63]
	ds_read_b128 v[162:165], v170 offset:5120
	v_mfma_f32_16x16x32_bf16 v[56:59], v[248:251], v[220:223], v[56:59]
	ds_read_b128 v[166:169], v172 offset:12288
	v_mfma_f32_16x16x32_bf16 v[52:55], v[252:255], v[220:223], v[52:55]
	ds_read_b128 v[200:203], v172 offset:13312
	v_mfma_f32_16x16x32_bf16 v[48:51], v[116:119], v[220:223], v[48:51]
	ds_read_b128 v[204:207], v172 offset:14336
	v_mfma_f32_16x16x32_bf16 v[44:47], v[244:247], v[224:227], v[44:47]
	ds_read_b128 v[208:211], v172 offset:15360
	v_mfma_f32_16x16x32_bf16 v[40:43], v[248:251], v[224:227], v[40:43]
	s_mov_b32 m0, s39
	v_mfma_f32_16x16x32_bf16 v[36:39], v[252:255], v[224:227], v[36:39]
	global_load_lds_dwordx4 v[124:125], off
	v_lshl_add_u64 v[124:125], v[124:125], 0, 64
	v_mfma_f32_16x16x32_bf16 v[32:35], v[116:119], v[224:227], v[32:35]
	s_add_u32 m0, s39, 0x1000
	v_mfma_f32_16x16x32_bf16 v[28:31], v[244:247], v[228:231], v[28:31]
	global_load_lds_dwordx4 v[122:123], off
	v_lshl_add_u64 v[122:123], v[122:123], 0, 64
	v_mfma_f32_16x16x32_bf16 v[24:27], v[248:251], v[228:231], v[24:27]
	s_add_u32 m0, s39, 0x2000
	v_mfma_f32_16x16x32_bf16 v[20:23], v[252:255], v[228:231], v[20:23]
	global_load_lds_dwordx4 v[120:121], off
	v_lshl_add_u64 v[120:121], v[120:121], 0, 64
	v_mfma_f32_16x16x32_bf16 v[16:19], v[116:119], v[228:231], v[16:19]
	s_add_u32 m0, s39, 0x3000
	v_mfma_f32_16x16x32_bf16 v[8:11], v[244:247], v[232:235], v[8:11]
	global_load_lds_dwordx4 v[236:237], off
	v_lshl_add_u64 v[236:237], v[236:237], 0, 64
	v_mfma_f32_16x16x32_bf16 v[4:7], v[248:251], v[232:235], v[4:7]
	s_add_u32 m0, s39, 0x4000
	v_mfma_f32_16x16x32_bf16 v[12:15], v[252:255], v[232:235], v[12:15]
	global_load_lds_dwordx4 v[126:127], off
	v_lshl_add_u64 v[126:127], v[126:127], 0, 64
	v_mfma_f32_16x16x32_bf16 v[0:3], v[116:119], v[232:235], v[0:3]
	s_add_i32 s41, s41, -1
	s_cmp_eq_u32 s41, 0
	s_cbranch_scc0 .Lk_ffo
	s_waitcnt lgkmcnt(0)
	v_mfma_f32_16x16x32_bf16 v[92:95], v[166:169], v[134:137], v[92:95]
	s_waitcnt vmcnt(10)
	s_barrier
	v_mfma_f32_16x16x32_bf16 v[88:91], v[200:203], v[134:137], v[88:91]
	s_cmp_eq_u32 s35, 0xf000
	s_cselect_b32 s38, s37, s36
	v_mfma_f32_16x16x32_bf16 v[84:87], v[204:207], v[134:137], v[84:87]
	v_add_u32_e32 v170, s38, v170
	v_add_u32_e32 v172, s38, v172
	s_add_u32 s35, s35, s38
	v_mfma_f32_16x16x32_bf16 v[80:83], v[208:211], v[134:137], v[80:83]
	ds_read_b128 v[212:215], v170
	v_mfma_f32_16x16x32_bf16 v[76:79], v[166:169], v[138:141], v[76:79]
	ds_read_b128 v[216:219], v170 offset:1024
	v_mfma_f32_16x16x32_bf16 v[72:75], v[200:203], v[138:141], v[72:75]
	ds_read_b128 v[220:223], v170 offset:2048
	v_mfma_f32_16x16x32_bf16 v[68:71], v[204:207], v[138:141], v[68:71]
	ds_read_b128 v[224:227], v170 offset:3072
	v_mfma_f32_16x16x32_bf16 v[64:67], v[208:211], v[138:141], v[64:67]
	ds_read_b128 v[228:231], v170 offset:4096
	v_mfma_f32_16x16x32_bf16 v[60:63], v[166:169], v[150:153], v[60:63]
	ds_read_b128 v[232:235], v170 offset:5120
	v_mfma_f32_16x16x32_bf16 v[56:59], v[200:203], v[150:153], v[56:59]
	ds_read_b128 v[244:247], v172 offset:12288
	v_mfma_f32_16x16x32_bf16 v[52:55], v[204:207], v[150:153], v[52:55]
	ds_read_b128 v[248:251], v172 offset:13312
	v_mfma_f32_16x16x32_bf16 v[48:51], v[208:211], v[150:153], v[48:51]
	ds_read_b128 v[252:255], v172 offset:14336
	v_mfma_f32_16x16x32_bf16 v[44:47], v[166:169], v[154:157], v[44:47]
	ds_read_b128 v[116:119], v172 offset:15360
	v_mfma_f32_16x16x32_bf16 v[40:43], v[200:203], v[154:157], v[40:43]
	v_mfma_f32_16x16x32_bf16 v[36:39], v[204:207], v[154:157], v[36:39]
	v_mfma_f32_16x16x32_bf16 v[32:35], v[208:211], v[154:157], v[32:35]
	v_mfma_f32_16x16x32_bf16 v[28:31], v[166:169], v[158:161], v[28:31]
	v_mfma_f32_16x16x32_bf16 v[24:27], v[200:203], v[158:161], v[24:27]
	v_mfma_f32_16x16x32_bf16 v[20:23], v[204:207], v[158:161], v[20:23]
	v_mfma_f32_16x16x32_bf16 v[16:19], v[208:211], v[158:161], v[16:19]
	v_mfma_f32_16x16x32_bf16 v[8:11], v[166:169], v[162:165], v[8:11]
	v_mfma_f32_16x16x32_bf16 v[4:7], v[200:203], v[162:165], v[4:7]
	v_mfma_f32_16x16x32_bf16 v[12:15], v[204:207], v[162:165], v[12:15]
	v_mfma_f32_16x16x32_bf16 v[0:3], v[208:211], v[162:165], v[0:3]
	s_waitcnt lgkmcnt(0)
	v_mfma_f32_16x16x32_bf16 v[92:95], v[244:247], v[212:215], v[92:95]
	s_waitcnt vmcnt(5)
	s_barrier
	v_mfma_f32_16x16x32_bf16 v[88:91], v[248:251], v[212:215], v[88:91]
	s_cmp_eq_u32 s35, 0xf000
	s_cselect_b32 s38, s37, s36
	v_mfma_f32_16x16x32_bf16 v[84:87], v[252:255], v[212:215], v[84:87]
	v_add_u32_e32 v170, s38, v170
	v_add_u32_e32 v172, s38, v172
	s_add_u32 s35, s35, s38
	v_mfma_f32_16x16x32_bf16 v[80:83], v[116:119], v[212:215], v[80:83]
	ds_read_b128 v[134:137], v170
	v_mfma_f32_16x16x32_bf16 v[76:79], v[244:247], v[216:219], v[76:79]
	ds_read_b128 v[138:141], v170 offset:1024
	v_mfma_f32_16x16x32_bf16 v[72:75], v[248:251], v[216:219], v[72:75]
	ds_read_b128 v[150:153], v170 offset:2048
	v_mfma_f32_16x16x32_bf16 v[68:71], v[252:255], v[216:219], v[68:71]
	ds_read_b128 v[154:157], v170 offset:3072
	v_mfma_f32_16x16x32_bf16 v[64:67], v[116:119], v[216:219], v[64:67]
	ds_read_b128 v[158:161], v170 offset:4096
	v_mfma_f32_16x16x32_bf16 v[60:63], v[244:247], v[220:223], v[60:63]
	ds_read_b128 v[162:165], v170 offset:5120
	v_mfma_f32_16x16x32_bf16 v[56:59], v[248:251], v[220:223], v[56:59]
	ds_read_b128 v[166:169], v172 offset:12288
	v_mfma_f32_16x16x32_bf16 v[52:55], v[252:255], v[220:223], v[52:55]
	ds_read_b128 v[200:203], v172 offset:13312
	v_mfma_f32_16x16x32_bf16 v[48:51], v[116:119], v[220:223], v[48:51]
	ds_read_b128 v[204:207], v172 offset:14336
	v_mfma_f32_16x16x32_bf16 v[44:47], v[244:247], v[224:227], v[44:47]
	ds_read_b128 v[208:211], v172 offset:15360
	v_mfma_f32_16x16x32_bf16 v[40:43], v[248:251], v[224:227], v[40:43]
	v_mfma_f32_16x16x32_bf16 v[36:39], v[252:255], v[224:227], v[36:39]
	v_mfma_f32_16x16x32_bf16 v[32:35], v[116:119], v[224:227], v[32:35]
	v_mfma_f32_16x16x32_bf16 v[28:31], v[244:247], v[228:231], v[28:31]
	v_mfma_f32_16x16x32_bf16 v[24:27], v[248:251], v[228:231], v[24:27]
	v_mfma_f32_16x16x32_bf16 v[20:23], v[252:255], v[228:231], v[20:23]
	v_mfma_f32_16x16x32_bf16 v[16:19], v[116:119], v[228:231], v[16:19]
	v_mfma_f32_16x16x32_bf16 v[8:11], v[244:247], v[232:235], v[8:11]
	v_mfma_f32_16x16x32_bf16 v[4:7], v[248:251], v[232:235], v[4:7]
	v_mfma_f32_16x16x32_bf16 v[12:15], v[252:255], v[232:235], v[12:15]
	v_mfma_f32_16x16x32_bf16 v[0:3], v[116:119], v[232:235], v[0:3]
	s_waitcnt lgkmcnt(0)
	v_mfma_f32_16x16x32_bf16 v[92:95], v[166:169], v[134:137], v[92:95]
	s_waitcnt vmcnt(0)
	s_barrier
	v_mfma_f32_16x16x32_bf16 v[88:91], v[200:203], v[134:137], v[88:91]
	s_cmp_eq_u32 s35, 0xf000
	s_cselect_b32 s38, s37, s36
	v_mfma_f32_16x16x32_bf16 v[84:87], v[204:207], v[134:137], v[84:87]
	v_add_u32_e32 v170, s38, v170
	v_add_u32_e32 v172, s38, v172
	s_add_u32 s35, s35, s38
	v_mfma_f32_16x16x32_bf16 v[80:83], v[208:211], v[134:137], v[80:83]
	ds_read_b128 v[212:215], v170
	v_mfma_f32_16x16x32_bf16 v[76:79], v[166:169], v[138:141], v[76:79]
	ds_read_b128 v[216:219], v170 offset:1024
	v_mfma_f32_16x16x32_bf16 v[72:75], v[200:203], v[138:141], v[72:75]
	ds_read_b128 v[220:223], v170 offset:2048
	v_mfma_f32_16x16x32_bf16 v[68:71], v[204:207], v[138:141], v[68:71]
	ds_read_b128 v[224:227], v170 offset:3072
	v_mfma_f32_16x16x32_bf16 v[64:67], v[208:211], v[138:141], v[64:67]
	ds_read_b128 v[228:231], v170 offset:4096
	v_mfma_f32_16x16x32_bf16 v[60:63], v[166:169], v[150:153], v[60:63]
	ds_read_b128 v[232:235], v170 offset:5120
	v_mfma_f32_16x16x32_bf16 v[56:59], v[200:203], v[150:153], v[56:59]
	ds_read_b128 v[244:247], v172 offset:12288
	v_mfma_f32_16x16x32_bf16 v[52:55], v[204:207], v[150:153], v[52:55]
	ds_read_b128 v[248:251], v172 offset:13312
	v_mfma_f32_16x16x32_bf16 v[48:51], v[208:211], v[150:153], v[48:51]
	ds_read_b128 v[252:255], v172 offset:14336
	v_mfma_f32_16x16x32_bf16 v[44:47], v[166:169], v[154:157], v[44:47]
	ds_read_b128 v[116:119], v172 offset:15360
	v_mfma_f32_16x16x32_bf16 v[40:43], v[200:203], v[154:157], v[40:43]
	v_mfma_f32_16x16x32_bf16 v[36:39], v[204:207], v[154:157], v[36:39]
	v_mfma_f32_16x16x32_bf16 v[32:35], v[208:211], v[154:157], v[32:35]
	v_mfma_f32_16x16x32_bf16 v[28:31], v[166:169], v[158:161], v[28:31]
	v_mfma_f32_16x16x32_bf16 v[24:27], v[200:203], v[158:161], v[24:27]
	v_mfma_f32_16x16x32_bf16 v[20:23], v[204:207], v[158:161], v[20:23]
	v_mfma_f32_16x16x32_bf16 v[16:19], v[208:211], v[158:161], v[16:19]
	v_mfma_f32_16x16x32_bf16 v[8:11], v[166:169], v[162:165], v[8:11]
	v_mfma_f32_16x16x32_bf16 v[4:7], v[200:203], v[162:165], v[4:7]
	v_mfma_f32_16x16x32_bf16 v[12:15], v[204:207], v[162:165], v[12:15]
	v_mfma_f32_16x16x32_bf16 v[0:3], v[208:211], v[162:165], v[0:3]
	s_waitcnt lgkmcnt(0)
	v_mfma_f32_16x16x32_bf16 v[92:95], v[244:247], v[212:215], v[92:95]
	v_mfma_f32_16x16x32_bf16 v[88:91], v[248:251], v[212:215], v[88:91]
	v_mfma_f32_16x16x32_bf16 v[84:87], v[252:255], v[212:215], v[84:87]
	v_mfma_f32_16x16x32_bf16 v[80:83], v[116:119], v[212:215], v[80:83]
	v_mfma_f32_16x16x32_bf16 v[76:79], v[244:247], v[216:219], v[76:79]
	v_mfma_f32_16x16x32_bf16 v[72:75], v[248:251], v[216:219], v[72:75]
	v_mfma_f32_16x16x32_bf16 v[68:71], v[252:255], v[216:219], v[68:71]
	v_mfma_f32_16x16x32_bf16 v[64:67], v[116:119], v[216:219], v[64:67]
	v_mfma_f32_16x16x32_bf16 v[60:63], v[244:247], v[220:223], v[60:63]
	v_mfma_f32_16x16x32_bf16 v[56:59], v[248:251], v[220:223], v[56:59]
	v_mfma_f32_16x16x32_bf16 v[52:55], v[252:255], v[220:223], v[52:55]
	v_mfma_f32_16x16x32_bf16 v[48:51], v[116:119], v[220:223], v[48:51]
	v_mfma_f32_16x16x32_bf16 v[44:47], v[244:247], v[224:227], v[44:47]
	v_mfma_f32_16x16x32_bf16 v[40:43], v[248:251], v[224:227], v[40:43]
	v_mfma_f32_16x16x32_bf16 v[36:39], v[252:255], v[224:227], v[36:39]
	v_mfma_f32_16x16x32_bf16 v[32:35], v[116:119], v[224:227], v[32:35]
	v_mfma_f32_16x16x32_bf16 v[28:31], v[244:247], v[228:231], v[28:31]
	v_mfma_f32_16x16x32_bf16 v[24:27], v[248:251], v[228:231], v[24:27]
	v_mfma_f32_16x16x32_bf16 v[20:23], v[252:255], v[228:231], v[20:23]
	v_mfma_f32_16x16x32_bf16 v[16:19], v[116:119], v[228:231], v[16:19]
	v_mfma_f32_16x16x32_bf16 v[8:11], v[244:247], v[232:235], v[8:11]
	v_mfma_f32_16x16x32_bf16 v[4:7], v[248:251], v[232:235], v[4:7]
	v_mfma_f32_16x16x32_bf16 v[12:15], v[252:255], v[232:235], v[12:15]
	v_mfma_f32_16x16x32_bf16 v[0:3], v[116:119], v[232:235], v[0:3]
	s_barrier
	v_mov_b32_e32 v170, s46
	v_mov_b32_e32 v172, s47
	ds_write_b32 v183, v170
	ds_write_b32 v184, v172
	s_waitcnt lgkmcnt(0)
	s_mulk_i32 s7, 0xc0
	s_add_i32 s5, s5, s51
	v_readlane_b32 s10, v242, 27
	v_readlane_b32 s11, v242, 28
	v_readlane_b32 s12, v242, 25
	v_readlane_b32 s13, v242, 26
	v_readlane_b32 s14, v243, 11
	v_readlane_b32 s15, v243, 12
	s_mov_b32 s8, 0x3fd744fd
	v_add_u32_e32 v236, s7, v145
	v_or_b32_e32 v254, s6, v146
	v_mov_b32_e32 v255, 0
	v_or_b32_e32 v237, v236, v133
	v_lshlrev_b64 v[254:255], 2, v[254:255]
	s_nop 0
	v_lshl_add_u64 v[250:251], s[12:13], 0, v[254:255]
	v_lshl_add_u64 v[252:253], s[14:15], 0, v[254:255]
	s_mov_b64 s[14:15], 0x5000
	v_lshl_add_u64 v[252:253], v[252:253], 0, s[14:15]
	v_readlane_b32 s12, v242, 29
	v_readlane_b32 s13, v242, 30
	v_lshl_add_u64 v[248:249], s[12:13], 0, v[254:255]
	v_readlane_b32 s12, v241, 9
	s_add_i32 s12, s12, -10
	s_mul_i32 s12, s12, 57
	s_lshr_b32 s12, s12, 9
	s_lshl_b32 s12, s12, 12
	v_readlane_b32 s14, v243, 59
	v_readlane_b32 s15, v243, 60
	s_add_u32 s14, s14, s12
	s_addc_u32 s15, s15, 0
	v_lshl_add_u64 v[224:225], s[14:15], 0, v[254:255]
	v_readlane_b32 s14, v243, 61
	v_readlane_b32 s15, v243, 62
	s_add_u32 s14, s14, s12
	s_addc_u32 s15, s15, 0
	v_lshl_add_u64 v[226:227], s[14:15], 0, v[254:255]
	global_load_dwordx4 v[96:99], v[224:225], off
	global_load_dwordx4 v[112:115], v[226:227], off
	global_load_dwordx4 v[100:103], v[224:225], off offset:64
	global_load_dwordx4 v[150:153], v[226:227], off offset:64
	global_load_dwordx4 v[104:107], v[224:225], off offset:128
	global_load_dwordx4 v[142:145], v[226:227], off offset:128
	global_load_dwordx4 v[108:111], v[224:225], off offset:192
	global_load_dwordx4 v[146:149], v[226:227], off offset:192
	v_mov_b32_e32 v255, 0
	v_add_u32_e32 v254, 0, v237
	v_add_u32_e32 v236, 0xfffff000, v254
	v_cmp_lt_i32_e32 vcc, 0xfff, v254
	v_lshrrev_b32_e32 v236, 10, v236
	v_lshlrev_b32_e32 v224, 3, v254
	v_lshlrev_b32_e32 v254, 12, v254
	v_add_u32_e32 v236, 1, v236
	v_mov_b32_e32 v225, 0
	v_cndmask_b32_e32 v236, 0, v236, vcc
	v_lshl_add_u64 v[224:225], v[224:225], 0, s[10:11]
	v_lshl_add_u64 v[228:229], v[254:255], 0, v[250:251]
	v_add_u32_e32 v236, s4, v236
	v_mad_i64_i32 v[232:233], s[0:1], v236, s33, v[252:253]
	global_load_dwordx2 v[132:133], v[224:225], off
	v_lshl_add_u64 v[224:225], v[254:255], 0, v[248:249]
	v_add_u32_e32 v254, 16, v237
	v_add_u32_e32 v236, 0xfffff000, v254
	v_cmp_lt_i32_e32 vcc, 0xfff, v254
	v_lshrrev_b32_e32 v236, 10, v236
	v_lshlrev_b32_e32 v226, 3, v254
	v_lshlrev_b32_e32 v254, 12, v254
	v_add_u32_e32 v236, 1, v236
	v_mov_b32_e32 v227, 0
	v_cndmask_b32_e32 v236, 0, v236, vcc
	v_lshl_add_u64 v[226:227], v[226:227], 0, s[10:11]
	v_lshl_add_u64 v[230:231], v[254:255], 0, v[250:251]
	v_add_u32_e32 v236, s4, v236
	v_mad_i64_i32 v[234:235], s[0:1], v236, s33, v[252:253]
	global_load_dword v128, v[226:227], off
	global_load_dword v170, v[226:227], off offset:4
	v_lshl_add_u64 v[226:227], v[254:255], 0, v[248:249]
	global_load_dwordx4 v[154:157], v[224:225], off
	global_load_dwordx4 v[116:119], v[232:233], off
	global_load_dwordx4 v[158:161], v[224:225], off offset:64
	global_load_dwordx4 v[120:123], v[232:233], off offset:64
	global_load_dwordx4 v[162:165], v[224:225], off offset:128
	global_load_dwordx4 v[124:127], v[232:233], off offset:128
	global_load_dwordx4 v[166:169], v[224:225], off offset:192
	global_load_dwordx4 v[134:137], v[232:233], off offset:192
	global_load_dwordx4 v[208:211], v[226:227], off
	global_load_dwordx4 v[138:141], v[234:235], off
	global_load_dwordx4 v[212:215], v[226:227], off offset:64
	global_load_dwordx4 v[200:203], v[234:235], off offset:64
	global_load_dwordx4 v[216:219], v[226:227], off offset:128
	global_load_dwordx4 v[204:207], v[234:235], off offset:128
	global_load_dwordx4 v[220:223], v[226:227], off offset:192
	global_load_dwordx4 v[244:247], v[234:235], off offset:192
	s_waitcnt vmcnt(0)
	v_pk_mul_f32 v[92:93], v[92:93], v[116:117]
	v_pk_add_f32 v[154:155], v[154:155], v[132:133] op_sel_hi:[1,0] neg_lo:[0,1] neg_hi:[0,1]
	v_pk_mul_f32 v[94:95], v[94:95], v[118:119]
	v_pk_add_f32 v[156:157], v[156:157], v[132:133] op_sel_hi:[1,0] neg_lo:[0,1] neg_hi:[0,1]
	v_pk_mul_f32 v[154:155], v[154:155], v[132:133] op_sel:[0,1] op_sel_hi:[1,1]
	v_pk_mul_f32 v[156:157], v[156:157], v[132:133] op_sel:[0,1] op_sel_hi:[1,1]
	v_pk_fma_f32 v[154:155], v[96:97], v[154:155], v[112:113]
	v_pk_fma_f32 v[156:157], v[98:99], v[156:157], v[114:115]
	v_pk_fma_f32 v[92:93], v[154:155], s[8:9], v[92:93] op_sel_hi:[1,0,1]
	v_pk_fma_f32 v[94:95], v[156:157], s[8:9], v[94:95] op_sel_hi:[1,0,1]
	global_store_dwordx4 v[228:229], v[92:95], off
	v_pk_mul_f32 v[88:89], v[88:89], v[120:121]
	v_pk_add_f32 v[158:159], v[158:159], v[132:133] op_sel_hi:[1,0] neg_lo:[0,1] neg_hi:[0,1]
	v_pk_mul_f32 v[90:91], v[90:91], v[122:123]
	v_pk_add_f32 v[160:161], v[160:161], v[132:133] op_sel_hi:[1,0] neg_lo:[0,1] neg_hi:[0,1]
	v_pk_mul_f32 v[158:159], v[158:159], v[132:133] op_sel:[0,1] op_sel_hi:[1,1]
	v_pk_mul_f32 v[160:161], v[160:161], v[132:133] op_sel:[0,1] op_sel_hi:[1,1]
	v_pk_fma_f32 v[158:159], v[100:101], v[158:159], v[150:151]
	v_pk_fma_f32 v[160:161], v[102:103], v[160:161], v[152:153]
	v_pk_fma_f32 v[88:89], v[158:159], s[8:9], v[88:89] op_sel_hi:[1,0,1]
	v_pk_fma_f32 v[90:91], v[160:161], s[8:9], v[90:91] op_sel_hi:[1,0,1]
	global_store_dwordx4 v[228:229], v[88:91], off offset:64
	v_pk_mul_f32 v[84:85], v[84:85], v[124:125]
	v_pk_add_f32 v[162:163], v[162:163], v[132:133] op_sel_hi:[1,0] neg_lo:[0,1] neg_hi:[0,1]
	v_pk_mul_f32 v[86:87], v[86:87], v[126:127]
	v_pk_add_f32 v[164:165], v[164:165], v[132:133] op_sel_hi:[1,0] neg_lo:[0,1] neg_hi:[0,1]
	v_pk_mul_f32 v[162:163], v[162:163], v[132:133] op_sel:[0,1] op_sel_hi:[1,1]
	v_pk_mul_f32 v[164:165], v[164:165], v[132:133] op_sel:[0,1] op_sel_hi:[1,1]
	v_pk_fma_f32 v[162:163], v[104:105], v[162:163], v[142:143]
	v_pk_fma_f32 v[164:165], v[106:107], v[164:165], v[144:145]
	v_pk_fma_f32 v[84:85], v[162:163], s[8:9], v[84:85] op_sel_hi:[1,0,1]
	v_pk_fma_f32 v[86:87], v[164:165], s[8:9], v[86:87] op_sel_hi:[1,0,1]
	global_store_dwordx4 v[228:229], v[84:87], off offset:128
	v_pk_mul_f32 v[80:81], v[80:81], v[134:135]
	v_pk_add_f32 v[166:167], v[166:167], v[132:133] op_sel_hi:[1,0] neg_lo:[0,1] neg_hi:[0,1]
	v_pk_mul_f32 v[82:83], v[82:83], v[136:137]
	v_pk_add_f32 v[168:169], v[168:169], v[132:133] op_sel_hi:[1,0] neg_lo:[0,1] neg_hi:[0,1]
	v_pk_mul_f32 v[166:167], v[166:167], v[132:133] op_sel:[0,1] op_sel_hi:[1,1]
	v_pk_mul_f32 v[168:169], v[168:169], v[132:133] op_sel:[0,1] op_sel_hi:[1,1]
	v_pk_fma_f32 v[166:167], v[108:109], v[166:167], v[146:147]
	v_pk_fma_f32 v[168:169], v[110:111], v[168:169], v[148:149]
	v_pk_fma_f32 v[80:81], v[166:167], s[8:9], v[80:81] op_sel_hi:[1,0,1]
	v_pk_fma_f32 v[82:83], v[168:169], s[8:9], v[82:83] op_sel_hi:[1,0,1]
	global_store_dwordx4 v[228:229], v[80:83], off offset:192
	v_pk_mul_f32 v[76:77], v[76:77], v[138:139]
	v_pk_add_f32 v[208:209], v[208:209], v[128:129] op_sel_hi:[1,0] neg_lo:[0,1] neg_hi:[0,1]
	v_pk_mul_f32 v[78:79], v[78:79], v[140:141]
	v_pk_add_f32 v[210:211], v[210:211], v[128:129] op_sel_hi:[1,0] neg_lo:[0,1] neg_hi:[0,1]
	v_pk_mul_f32 v[208:209], v[208:209], v[170:171] op_sel_hi:[1,0]
	v_pk_mul_f32 v[210:211], v[210:211], v[170:171] op_sel_hi:[1,0]
	v_pk_fma_f32 v[208:209], v[96:97], v[208:209], v[112:113]
	v_pk_fma_f32 v[210:211], v[98:99], v[210:211], v[114:115]
	v_pk_fma_f32 v[76:77], v[208:209], s[8:9], v[76:77] op_sel_hi:[1,0,1]
	v_pk_fma_f32 v[78:79], v[210:211], s[8:9], v[78:79] op_sel_hi:[1,0,1]
	global_store_dwordx4 v[230:231], v[76:79], off
	v_pk_mul_f32 v[72:73], v[72:73], v[200:201]
	v_pk_add_f32 v[212:213], v[212:213], v[128:129] op_sel_hi:[1,0] neg_lo:[0,1] neg_hi:[0,1]
	v_pk_mul_f32 v[74:75], v[74:75], v[202:203]
	v_pk_add_f32 v[214:215], v[214:215], v[128:129] op_sel_hi:[1,0] neg_lo:[0,1] neg_hi:[0,1]
	v_pk_mul_f32 v[212:213], v[212:213], v[170:171] op_sel_hi:[1,0]
	v_pk_mul_f32 v[214:215], v[214:215], v[170:171] op_sel_hi:[1,0]
	v_pk_fma_f32 v[212:213], v[100:101], v[212:213], v[150:151]
	v_pk_fma_f32 v[214:215], v[102:103], v[214:215], v[152:153]
	v_pk_fma_f32 v[72:73], v[212:213], s[8:9], v[72:73] op_sel_hi:[1,0,1]
	v_pk_fma_f32 v[74:75], v[214:215], s[8:9], v[74:75] op_sel_hi:[1,0,1]
	global_store_dwordx4 v[230:231], v[72:75], off offset:64
	v_pk_mul_f32 v[68:69], v[68:69], v[204:205]
	v_pk_add_f32 v[216:217], v[216:217], v[128:129] op_sel_hi:[1,0] neg_lo:[0,1] neg_hi:[0,1]
	v_pk_mul_f32 v[70:71], v[70:71], v[206:207]
	v_pk_add_f32 v[218:219], v[218:219], v[128:129] op_sel_hi:[1,0] neg_lo:[0,1] neg_hi:[0,1]
	v_pk_mul_f32 v[216:217], v[216:217], v[170:171] op_sel_hi:[1,0]
	v_pk_mul_f32 v[218:219], v[218:219], v[170:171] op_sel_hi:[1,0]
	v_pk_fma_f32 v[216:217], v[104:105], v[216:217], v[142:143]
	v_pk_fma_f32 v[218:219], v[106:107], v[218:219], v[144:145]
	v_pk_fma_f32 v[68:69], v[216:217], s[8:9], v[68:69] op_sel_hi:[1,0,1]
	v_pk_fma_f32 v[70:71], v[218:219], s[8:9], v[70:71] op_sel_hi:[1,0,1]
	global_store_dwordx4 v[230:231], v[68:71], off offset:128
	v_pk_mul_f32 v[64:65], v[64:65], v[244:245]
	v_pk_add_f32 v[220:221], v[220:221], v[128:129] op_sel_hi:[1,0] neg_lo:[0,1] neg_hi:[0,1]
	v_pk_mul_f32 v[66:67], v[66:67], v[246:247]
	v_pk_add_f32 v[222:223], v[222:223], v[128:129] op_sel_hi:[1,0] neg_lo:[0,1] neg_hi:[0,1]
	v_pk_mul_f32 v[220:221], v[220:221], v[170:171] op_sel_hi:[1,0]
	v_pk_mul_f32 v[222:223], v[222:223], v[170:171] op_sel_hi:[1,0]
	v_pk_fma_f32 v[220:221], v[108:109], v[220:221], v[146:147]
	v_pk_fma_f32 v[222:223], v[110:111], v[222:223], v[148:149]
	v_pk_fma_f32 v[64:65], v[220:221], s[8:9], v[64:65] op_sel_hi:[1,0,1]
	v_pk_fma_f32 v[66:67], v[222:223], s[8:9], v[66:67] op_sel_hi:[1,0,1]
	global_store_dwordx4 v[230:231], v[64:67], off offset:192
	v_add_u32_e32 v254, 32, v237
	v_add_u32_e32 v236, 0xfffff000, v254
	v_cmp_lt_i32_e32 vcc, 0xfff, v254
	v_lshrrev_b32_e32 v236, 10, v236
	v_lshlrev_b32_e32 v224, 3, v254
	v_lshlrev_b32_e32 v254, 12, v254
	v_add_u32_e32 v236, 1, v236
	v_mov_b32_e32 v225, 0
	v_cndmask_b32_e32 v236, 0, v236, vcc
	v_lshl_add_u64 v[224:225], v[224:225], 0, s[10:11]
	v_lshl_add_u64 v[228:229], v[254:255], 0, v[250:251]
	v_add_u32_e32 v236, s4, v236
	v_mad_i64_i32 v[232:233], s[0:1], v236, s33, v[252:253]
	global_load_dwordx2 v[132:133], v[224:225], off
	v_lshl_add_u64 v[224:225], v[254:255], 0, v[248:249]
	v_add_u32_e32 v254, 48, v237
	v_add_u32_e32 v236, 0xfffff000, v254
	v_cmp_lt_i32_e32 vcc, 0xfff, v254
	v_lshrrev_b32_e32 v236, 10, v236
	v_lshlrev_b32_e32 v226, 3, v254
	v_lshlrev_b32_e32 v254, 12, v254
	v_add_u32_e32 v236, 1, v236
	v_mov_b32_e32 v227, 0
	v_cndmask_b32_e32 v236, 0, v236, vcc
	v_lshl_add_u64 v[226:227], v[226:227], 0, s[10:11]
	v_lshl_add_u64 v[230:231], v[254:255], 0, v[250:251]
	v_add_u32_e32 v236, s4, v236
	v_mad_i64_i32 v[234:235], s[0:1], v236, s33, v[252:253]
	global_load_dword v128, v[226:227], off
	global_load_dword v170, v[226:227], off offset:4
	v_lshl_add_u64 v[226:227], v[254:255], 0, v[248:249]
	global_load_dwordx4 v[154:157], v[224:225], off
	global_load_dwordx4 v[116:119], v[232:233], off
	global_load_dwordx4 v[158:161], v[224:225], off offset:64
	global_load_dwordx4 v[120:123], v[232:233], off offset:64
	global_load_dwordx4 v[162:165], v[224:225], off offset:128
	global_load_dwordx4 v[124:127], v[232:233], off offset:128
	global_load_dwordx4 v[166:169], v[224:225], off offset:192
	global_load_dwordx4 v[134:137], v[232:233], off offset:192
	global_load_dwordx4 v[208:211], v[226:227], off
	global_load_dwordx4 v[138:141], v[234:235], off
	global_load_dwordx4 v[212:215], v[226:227], off offset:64
	global_load_dwordx4 v[200:203], v[234:235], off offset:64
	global_load_dwordx4 v[216:219], v[226:227], off offset:128
	global_load_dwordx4 v[204:207], v[234:235], off offset:128
	global_load_dwordx4 v[220:223], v[226:227], off offset:192
	global_load_dwordx4 v[244:247], v[234:235], off offset:192
	s_waitcnt vmcnt(0)
	v_pk_mul_f32 v[60:61], v[60:61], v[116:117]
	v_pk_add_f32 v[154:155], v[154:155], v[132:133] op_sel_hi:[1,0] neg_lo:[0,1] neg_hi:[0,1]
	v_pk_mul_f32 v[62:63], v[62:63], v[118:119]
	v_pk_add_f32 v[156:157], v[156:157], v[132:133] op_sel_hi:[1,0] neg_lo:[0,1] neg_hi:[0,1]
	v_pk_mul_f32 v[154:155], v[154:155], v[132:133] op_sel:[0,1] op_sel_hi:[1,1]
	v_pk_mul_f32 v[156:157], v[156:157], v[132:133] op_sel:[0,1] op_sel_hi:[1,1]
	v_pk_fma_f32 v[154:155], v[96:97], v[154:155], v[112:113]
	v_pk_fma_f32 v[156:157], v[98:99], v[156:157], v[114:115]
	v_pk_fma_f32 v[60:61], v[154:155], s[8:9], v[60:61] op_sel_hi:[1,0,1]
	v_pk_fma_f32 v[62:63], v[156:157], s[8:9], v[62:63] op_sel_hi:[1,0,1]
	global_store_dwordx4 v[228:229], v[60:63], off
	v_pk_mul_f32 v[56:57], v[56:57], v[120:121]
	v_pk_add_f32 v[158:159], v[158:159], v[132:133] op_sel_hi:[1,0] neg_lo:[0,1] neg_hi:[0,1]
	v_pk_mul_f32 v[58:59], v[58:59], v[122:123]
	v_pk_add_f32 v[160:161], v[160:161], v[132:133] op_sel_hi:[1,0] neg_lo:[0,1] neg_hi:[0,1]
	v_pk_mul_f32 v[158:159], v[158:159], v[132:133] op_sel:[0,1] op_sel_hi:[1,1]
	v_pk_mul_f32 v[160:161], v[160:161], v[132:133] op_sel:[0,1] op_sel_hi:[1,1]
	v_pk_fma_f32 v[158:159], v[100:101], v[158:159], v[150:151]
	v_pk_fma_f32 v[160:161], v[102:103], v[160:161], v[152:153]
	v_pk_fma_f32 v[56:57], v[158:159], s[8:9], v[56:57] op_sel_hi:[1,0,1]
	v_pk_fma_f32 v[58:59], v[160:161], s[8:9], v[58:59] op_sel_hi:[1,0,1]
	global_store_dwordx4 v[228:229], v[56:59], off offset:64
	v_pk_mul_f32 v[52:53], v[52:53], v[124:125]
	v_pk_add_f32 v[162:163], v[162:163], v[132:133] op_sel_hi:[1,0] neg_lo:[0,1] neg_hi:[0,1]
	v_pk_mul_f32 v[54:55], v[54:55], v[126:127]
	v_pk_add_f32 v[164:165], v[164:165], v[132:133] op_sel_hi:[1,0] neg_lo:[0,1] neg_hi:[0,1]
	v_pk_mul_f32 v[162:163], v[162:163], v[132:133] op_sel:[0,1] op_sel_hi:[1,1]
	v_pk_mul_f32 v[164:165], v[164:165], v[132:133] op_sel:[0,1] op_sel_hi:[1,1]
	v_pk_fma_f32 v[162:163], v[104:105], v[162:163], v[142:143]
	v_pk_fma_f32 v[164:165], v[106:107], v[164:165], v[144:145]
	v_pk_fma_f32 v[52:53], v[162:163], s[8:9], v[52:53] op_sel_hi:[1,0,1]
	v_pk_fma_f32 v[54:55], v[164:165], s[8:9], v[54:55] op_sel_hi:[1,0,1]
	global_store_dwordx4 v[228:229], v[52:55], off offset:128
	v_pk_mul_f32 v[48:49], v[48:49], v[134:135]
	v_pk_add_f32 v[166:167], v[166:167], v[132:133] op_sel_hi:[1,0] neg_lo:[0,1] neg_hi:[0,1]
	v_pk_mul_f32 v[50:51], v[50:51], v[136:137]
	v_pk_add_f32 v[168:169], v[168:169], v[132:133] op_sel_hi:[1,0] neg_lo:[0,1] neg_hi:[0,1]
	v_pk_mul_f32 v[166:167], v[166:167], v[132:133] op_sel:[0,1] op_sel_hi:[1,1]
	v_pk_mul_f32 v[168:169], v[168:169], v[132:133] op_sel:[0,1] op_sel_hi:[1,1]
	v_pk_fma_f32 v[166:167], v[108:109], v[166:167], v[146:147]
	v_pk_fma_f32 v[168:169], v[110:111], v[168:169], v[148:149]
	v_pk_fma_f32 v[48:49], v[166:167], s[8:9], v[48:49] op_sel_hi:[1,0,1]
	v_pk_fma_f32 v[50:51], v[168:169], s[8:9], v[50:51] op_sel_hi:[1,0,1]
	global_store_dwordx4 v[228:229], v[48:51], off offset:192
	v_pk_mul_f32 v[44:45], v[44:45], v[138:139]
	v_pk_add_f32 v[208:209], v[208:209], v[128:129] op_sel_hi:[1,0] neg_lo:[0,1] neg_hi:[0,1]
	v_pk_mul_f32 v[46:47], v[46:47], v[140:141]
	v_pk_add_f32 v[210:211], v[210:211], v[128:129] op_sel_hi:[1,0] neg_lo:[0,1] neg_hi:[0,1]
	v_pk_mul_f32 v[208:209], v[208:209], v[170:171] op_sel_hi:[1,0]
	v_pk_mul_f32 v[210:211], v[210:211], v[170:171] op_sel_hi:[1,0]
	v_pk_fma_f32 v[208:209], v[96:97], v[208:209], v[112:113]
	v_pk_fma_f32 v[210:211], v[98:99], v[210:211], v[114:115]
	v_pk_fma_f32 v[44:45], v[208:209], s[8:9], v[44:45] op_sel_hi:[1,0,1]
	v_pk_fma_f32 v[46:47], v[210:211], s[8:9], v[46:47] op_sel_hi:[1,0,1]
	global_store_dwordx4 v[230:231], v[44:47], off
	v_pk_mul_f32 v[40:41], v[40:41], v[200:201]
	v_pk_add_f32 v[212:213], v[212:213], v[128:129] op_sel_hi:[1,0] neg_lo:[0,1] neg_hi:[0,1]
	v_pk_mul_f32 v[42:43], v[42:43], v[202:203]
	v_pk_add_f32 v[214:215], v[214:215], v[128:129] op_sel_hi:[1,0] neg_lo:[0,1] neg_hi:[0,1]
	v_pk_mul_f32 v[212:213], v[212:213], v[170:171] op_sel_hi:[1,0]
	v_pk_mul_f32 v[214:215], v[214:215], v[170:171] op_sel_hi:[1,0]
	v_pk_fma_f32 v[212:213], v[100:101], v[212:213], v[150:151]
	v_pk_fma_f32 v[214:215], v[102:103], v[214:215], v[152:153]
	v_pk_fma_f32 v[40:41], v[212:213], s[8:9], v[40:41] op_sel_hi:[1,0,1]
	v_pk_fma_f32 v[42:43], v[214:215], s[8:9], v[42:43] op_sel_hi:[1,0,1]
	global_store_dwordx4 v[230:231], v[40:43], off offset:64
	v_pk_mul_f32 v[36:37], v[36:37], v[204:205]
	v_pk_add_f32 v[216:217], v[216:217], v[128:129] op_sel_hi:[1,0] neg_lo:[0,1] neg_hi:[0,1]
	v_pk_mul_f32 v[38:39], v[38:39], v[206:207]
	v_pk_add_f32 v[218:219], v[218:219], v[128:129] op_sel_hi:[1,0] neg_lo:[0,1] neg_hi:[0,1]
	v_pk_mul_f32 v[216:217], v[216:217], v[170:171] op_sel_hi:[1,0]
	v_pk_mul_f32 v[218:219], v[218:219], v[170:171] op_sel_hi:[1,0]
	v_pk_fma_f32 v[216:217], v[104:105], v[216:217], v[142:143]
	v_pk_fma_f32 v[218:219], v[106:107], v[218:219], v[144:145]
	v_pk_fma_f32 v[36:37], v[216:217], s[8:9], v[36:37] op_sel_hi:[1,0,1]
	v_pk_fma_f32 v[38:39], v[218:219], s[8:9], v[38:39] op_sel_hi:[1,0,1]
	global_store_dwordx4 v[230:231], v[36:39], off offset:128
	v_pk_mul_f32 v[32:33], v[32:33], v[244:245]
	v_pk_add_f32 v[220:221], v[220:221], v[128:129] op_sel_hi:[1,0] neg_lo:[0,1] neg_hi:[0,1]
	v_pk_mul_f32 v[34:35], v[34:35], v[246:247]
	v_pk_add_f32 v[222:223], v[222:223], v[128:129] op_sel_hi:[1,0] neg_lo:[0,1] neg_hi:[0,1]
	v_pk_mul_f32 v[220:221], v[220:221], v[170:171] op_sel_hi:[1,0]
	v_pk_mul_f32 v[222:223], v[222:223], v[170:171] op_sel_hi:[1,0]
	v_pk_fma_f32 v[220:221], v[108:109], v[220:221], v[146:147]
	v_pk_fma_f32 v[222:223], v[110:111], v[222:223], v[148:149]
	v_pk_fma_f32 v[32:33], v[220:221], s[8:9], v[32:33] op_sel_hi:[1,0,1]
	v_pk_fma_f32 v[34:35], v[222:223], s[8:9], v[34:35] op_sel_hi:[1,0,1]
	global_store_dwordx4 v[230:231], v[32:35], off offset:192
	v_add_u32_e32 v254, 64, v237
	v_add_u32_e32 v236, 0xfffff000, v254
	v_cmp_lt_i32_e32 vcc, 0xfff, v254
	v_lshrrev_b32_e32 v236, 10, v236
	v_lshlrev_b32_e32 v224, 3, v254
	v_lshlrev_b32_e32 v254, 12, v254
	v_add_u32_e32 v236, 1, v236
	v_mov_b32_e32 v225, 0
	v_cndmask_b32_e32 v236, 0, v236, vcc
	v_lshl_add_u64 v[224:225], v[224:225], 0, s[10:11]
	v_lshl_add_u64 v[228:229], v[254:255], 0, v[250:251]
	v_add_u32_e32 v236, s4, v236
	v_mad_i64_i32 v[232:233], s[0:1], v236, s33, v[252:253]
	global_load_dwordx2 v[132:133], v[224:225], off
	v_lshl_add_u64 v[224:225], v[254:255], 0, v[248:249]
	v_add_u32_e32 v254, 80, v237
	v_add_u32_e32 v236, 0xfffff000, v254
	v_cmp_lt_i32_e32 vcc, 0xfff, v254
	v_lshrrev_b32_e32 v236, 10, v236
	v_lshlrev_b32_e32 v226, 3, v254
	v_lshlrev_b32_e32 v254, 12, v254
	v_add_u32_e32 v236, 1, v236
	v_mov_b32_e32 v227, 0
	v_cndmask_b32_e32 v236, 0, v236, vcc
	v_lshl_add_u64 v[226:227], v[226:227], 0, s[10:11]
	v_lshl_add_u64 v[230:231], v[254:255], 0, v[250:251]
	v_add_u32_e32 v236, s4, v236
	v_mad_i64_i32 v[234:235], s[0:1], v236, s33, v[252:253]
	global_load_dword v128, v[226:227], off
	global_load_dword v170, v[226:227], off offset:4
	v_lshl_add_u64 v[226:227], v[254:255], 0, v[248:249]
	global_load_dwordx4 v[154:157], v[224:225], off
	global_load_dwordx4 v[116:119], v[232:233], off
	global_load_dwordx4 v[158:161], v[224:225], off offset:64
	global_load_dwordx4 v[120:123], v[232:233], off offset:64
	global_load_dwordx4 v[162:165], v[224:225], off offset:128
	global_load_dwordx4 v[124:127], v[232:233], off offset:128
	global_load_dwordx4 v[166:169], v[224:225], off offset:192
	global_load_dwordx4 v[134:137], v[232:233], off offset:192
	global_load_dwordx4 v[208:211], v[226:227], off
	global_load_dwordx4 v[138:141], v[234:235], off
	global_load_dwordx4 v[212:215], v[226:227], off offset:64
	global_load_dwordx4 v[200:203], v[234:235], off offset:64
	global_load_dwordx4 v[216:219], v[226:227], off offset:128
	global_load_dwordx4 v[204:207], v[234:235], off offset:128
	global_load_dwordx4 v[220:223], v[226:227], off offset:192
	global_load_dwordx4 v[244:247], v[234:235], off offset:192
	s_waitcnt vmcnt(0)
	v_pk_mul_f32 v[28:29], v[28:29], v[116:117]
	v_pk_add_f32 v[154:155], v[154:155], v[132:133] op_sel_hi:[1,0] neg_lo:[0,1] neg_hi:[0,1]
	v_pk_mul_f32 v[30:31], v[30:31], v[118:119]
	v_pk_add_f32 v[156:157], v[156:157], v[132:133] op_sel_hi:[1,0] neg_lo:[0,1] neg_hi:[0,1]
	v_pk_mul_f32 v[154:155], v[154:155], v[132:133] op_sel:[0,1] op_sel_hi:[1,1]
	v_pk_mul_f32 v[156:157], v[156:157], v[132:133] op_sel:[0,1] op_sel_hi:[1,1]
	v_pk_fma_f32 v[154:155], v[96:97], v[154:155], v[112:113]
	v_pk_fma_f32 v[156:157], v[98:99], v[156:157], v[114:115]
	v_pk_fma_f32 v[28:29], v[154:155], s[8:9], v[28:29] op_sel_hi:[1,0,1]
	v_pk_fma_f32 v[30:31], v[156:157], s[8:9], v[30:31] op_sel_hi:[1,0,1]
	global_store_dwordx4 v[228:229], v[28:31], off
	v_pk_mul_f32 v[24:25], v[24:25], v[120:121]
	v_pk_add_f32 v[158:159], v[158:159], v[132:133] op_sel_hi:[1,0] neg_lo:[0,1] neg_hi:[0,1]
	v_pk_mul_f32 v[26:27], v[26:27], v[122:123]
	v_pk_add_f32 v[160:161], v[160:161], v[132:133] op_sel_hi:[1,0] neg_lo:[0,1] neg_hi:[0,1]
	v_pk_mul_f32 v[158:159], v[158:159], v[132:133] op_sel:[0,1] op_sel_hi:[1,1]
	v_pk_mul_f32 v[160:161], v[160:161], v[132:133] op_sel:[0,1] op_sel_hi:[1,1]
	v_pk_fma_f32 v[158:159], v[100:101], v[158:159], v[150:151]
	v_pk_fma_f32 v[160:161], v[102:103], v[160:161], v[152:153]
	v_pk_fma_f32 v[24:25], v[158:159], s[8:9], v[24:25] op_sel_hi:[1,0,1]
	v_pk_fma_f32 v[26:27], v[160:161], s[8:9], v[26:27] op_sel_hi:[1,0,1]
	global_store_dwordx4 v[228:229], v[24:27], off offset:64
	v_pk_mul_f32 v[20:21], v[20:21], v[124:125]
	v_pk_add_f32 v[162:163], v[162:163], v[132:133] op_sel_hi:[1,0] neg_lo:[0,1] neg_hi:[0,1]
	v_pk_mul_f32 v[22:23], v[22:23], v[126:127]
	v_pk_add_f32 v[164:165], v[164:165], v[132:133] op_sel_hi:[1,0] neg_lo:[0,1] neg_hi:[0,1]
	v_pk_mul_f32 v[162:163], v[162:163], v[132:133] op_sel:[0,1] op_sel_hi:[1,1]
	v_pk_mul_f32 v[164:165], v[164:165], v[132:133] op_sel:[0,1] op_sel_hi:[1,1]
	v_pk_fma_f32 v[162:163], v[104:105], v[162:163], v[142:143]
	v_pk_fma_f32 v[164:165], v[106:107], v[164:165], v[144:145]
	v_pk_fma_f32 v[20:21], v[162:163], s[8:9], v[20:21] op_sel_hi:[1,0,1]
	v_pk_fma_f32 v[22:23], v[164:165], s[8:9], v[22:23] op_sel_hi:[1,0,1]
	global_store_dwordx4 v[228:229], v[20:23], off offset:128
	v_pk_mul_f32 v[16:17], v[16:17], v[134:135]
	v_pk_add_f32 v[166:167], v[166:167], v[132:133] op_sel_hi:[1,0] neg_lo:[0,1] neg_hi:[0,1]
	v_pk_mul_f32 v[18:19], v[18:19], v[136:137]
	v_pk_add_f32 v[168:169], v[168:169], v[132:133] op_sel_hi:[1,0] neg_lo:[0,1] neg_hi:[0,1]
	v_pk_mul_f32 v[166:167], v[166:167], v[132:133] op_sel:[0,1] op_sel_hi:[1,1]
	v_pk_mul_f32 v[168:169], v[168:169], v[132:133] op_sel:[0,1] op_sel_hi:[1,1]
	v_pk_fma_f32 v[166:167], v[108:109], v[166:167], v[146:147]
	v_pk_fma_f32 v[168:169], v[110:111], v[168:169], v[148:149]
	v_pk_fma_f32 v[16:17], v[166:167], s[8:9], v[16:17] op_sel_hi:[1,0,1]
	v_pk_fma_f32 v[18:19], v[168:169], s[8:9], v[18:19] op_sel_hi:[1,0,1]
	global_store_dwordx4 v[228:229], v[16:19], off offset:192
	v_pk_mul_f32 v[8:9], v[8:9], v[138:139]
	v_pk_add_f32 v[208:209], v[208:209], v[128:129] op_sel_hi:[1,0] neg_lo:[0,1] neg_hi:[0,1]
	v_pk_mul_f32 v[10:11], v[10:11], v[140:141]
	v_pk_add_f32 v[210:211], v[210:211], v[128:129] op_sel_hi:[1,0] neg_lo:[0,1] neg_hi:[0,1]
	v_pk_mul_f32 v[208:209], v[208:209], v[170:171] op_sel_hi:[1,0]
	v_pk_mul_f32 v[210:211], v[210:211], v[170:171] op_sel_hi:[1,0]
	v_pk_fma_f32 v[208:209], v[96:97], v[208:209], v[112:113]
	v_pk_fma_f32 v[210:211], v[98:99], v[210:211], v[114:115]
	v_pk_fma_f32 v[8:9], v[208:209], s[8:9], v[8:9] op_sel_hi:[1,0,1]
	v_pk_fma_f32 v[10:11], v[210:211], s[8:9], v[10:11] op_sel_hi:[1,0,1]
	global_store_dwordx4 v[230:231], v[8:11], off
	v_pk_mul_f32 v[4:5], v[4:5], v[200:201]
	v_pk_add_f32 v[212:213], v[212:213], v[128:129] op_sel_hi:[1,0] neg_lo:[0,1] neg_hi:[0,1]
	v_pk_mul_f32 v[6:7], v[6:7], v[202:203]
	v_pk_add_f32 v[214:215], v[214:215], v[128:129] op_sel_hi:[1,0] neg_lo:[0,1] neg_hi:[0,1]
	v_pk_mul_f32 v[212:213], v[212:213], v[170:171] op_sel_hi:[1,0]
	v_pk_mul_f32 v[214:215], v[214:215], v[170:171] op_sel_hi:[1,0]
	v_pk_fma_f32 v[212:213], v[100:101], v[212:213], v[150:151]
	v_pk_fma_f32 v[214:215], v[102:103], v[214:215], v[152:153]
	v_pk_fma_f32 v[4:5], v[212:213], s[8:9], v[4:5] op_sel_hi:[1,0,1]
	v_pk_fma_f32 v[6:7], v[214:215], s[8:9], v[6:7] op_sel_hi:[1,0,1]
	global_store_dwordx4 v[230:231], v[4:7], off offset:64
	v_pk_mul_f32 v[12:13], v[12:13], v[204:205]
	v_pk_add_f32 v[216:217], v[216:217], v[128:129] op_sel_hi:[1,0] neg_lo:[0,1] neg_hi:[0,1]
	v_pk_mul_f32 v[14:15], v[14:15], v[206:207]
	v_pk_add_f32 v[218:219], v[218:219], v[128:129] op_sel_hi:[1,0] neg_lo:[0,1] neg_hi:[0,1]
	v_pk_mul_f32 v[216:217], v[216:217], v[170:171] op_sel_hi:[1,0]
	v_pk_mul_f32 v[218:219], v[218:219], v[170:171] op_sel_hi:[1,0]
	v_pk_fma_f32 v[216:217], v[104:105], v[216:217], v[142:143]
	v_pk_fma_f32 v[218:219], v[106:107], v[218:219], v[144:145]
	v_pk_fma_f32 v[12:13], v[216:217], s[8:9], v[12:13] op_sel_hi:[1,0,1]
	v_pk_fma_f32 v[14:15], v[218:219], s[8:9], v[14:15] op_sel_hi:[1,0,1]
	global_store_dwordx4 v[230:231], v[12:15], off offset:128
	v_pk_mul_f32 v[0:1], v[0:1], v[244:245]
	v_pk_add_f32 v[220:221], v[220:221], v[128:129] op_sel_hi:[1,0] neg_lo:[0,1] neg_hi:[0,1]
	v_pk_mul_f32 v[2:3], v[2:3], v[246:247]
	v_pk_add_f32 v[222:223], v[222:223], v[128:129] op_sel_hi:[1,0] neg_lo:[0,1] neg_hi:[0,1]
	v_pk_mul_f32 v[220:221], v[220:221], v[170:171] op_sel_hi:[1,0]
	v_pk_mul_f32 v[222:223], v[222:223], v[170:171] op_sel_hi:[1,0]
	v_pk_fma_f32 v[220:221], v[108:109], v[220:221], v[146:147]
	v_pk_fma_f32 v[222:223], v[110:111], v[222:223], v[148:149]
	v_pk_fma_f32 v[0:1], v[220:221], s[8:9], v[0:1] op_sel_hi:[1,0,1]
	v_pk_fma_f32 v[2:3], v[222:223], s[8:9], v[2:3] op_sel_hi:[1,0,1]
	global_store_dwordx4 v[230:231], v[0:3], off offset:192
	v_readlane_b32 s9, v242, 26
	v_readlane_b32 s10, v242, 27
	v_readlane_b32 s11, v242, 28
	v_readlane_b32 s12, v242, 29
	v_readlane_b32 s13, v242, 30
	v_readlane_b32 s14, v242, 31
	v_readlane_b32 s15, v242, 32
	v_readlane_b32 s16, v242, 33
	v_readlane_b32 s17, v242, 34
	v_readlane_b32 s18, v242, 35
	v_readlane_b32 s19, v242, 36
	v_readlane_b32 s20, v242, 37
	v_readlane_b32 s21, v242, 38
	v_readlane_b32 s22, v242, 39
	v_readlane_b32 s23, v242, 40
	s_mov_b64 s[24:25], 0x5000
	s_movk_i32 s6, 0xfff
	s_waitcnt lgkmcnt(0)
	s_barrier
	s_cmpk_gt_i32 s5, 0xff
	s_cbranch_scc0 .LBB0_52

.LBB0_127:
	s_ashr_i32 s0, s9, 31
	s_lshr_b32 s0, s0, 27
	s_add_i32 s1, s9, s0
	s_and_b32 s0, s1, 0x3ffffe0
	s_sub_i32 s0, s9, s0
	s_mulk_i32 s0, 0xc0
	s_lshl_b32 s1, s1, 2
	s_and_b32 s4, s1, 0xffffff80
	s_ashr_i32 s1, s0, 31
	s_lshl_b64 s[6:7], s[0:1], 11
	v_lshl_add_u64 v[0:1], v[98:99], 0, s[6:7]
	v_readfirstlane_b32 s1, v142
	s_ashr_i32 s5, s4, 31
	v_lshl_add_u64 v[4:5], v[0:1], 0, v[112:113]
	s_mov_b32 m0, s1
	v_readfirstlane_b32 s1, v143
	s_lshl_b64 s[12:13], s[4:5], 11
	global_load_lds_dwordx4 v[4:5], off
	v_lshl_add_u64 v[6:7], v[0:1], 0, v[114:115]
	s_mov_b32 m0, s1
	v_readfirstlane_b32 s1, v144
	v_add_u32_e32 v10, 0x3000, v142
	v_lshl_add_u64 v[2:3], v[100:101], 0, s[12:13]
	global_load_lds_dwordx4 v[6:7], off
	v_lshl_add_u64 v[0:1], v[0:1], 0, v[96:97]
	s_mov_b32 m0, s1
	v_readfirstlane_b32 s1, v10
	v_add_u32_e32 v10, 0x4000, v142
	global_load_lds_dwordx4 v[0:1], off
	v_lshl_add_u64 v[8:9], v[2:3], 0, v[112:113]
	s_mov_b32 m0, s1
	v_readfirstlane_b32 s1, v10
	v_add_u32_e32 v10, 0x5000, v142
	global_load_lds_dwordx4 v[8:9], off
	v_lshl_add_u64 v[2:3], v[2:3], 0, v[114:115]
	s_mov_b32 m0, s1
	v_readfirstlane_b32 s1, v10
	global_load_lds_dwordx4 v[2:3], off
	v_lshl_add_u64 v[4:5], v[4:5], 0, 64
	s_mov_b32 m0, s1
	v_lshl_add_u64 v[0:1], v[0:1], 0, 64
	global_load_lds_dwordx4 v[4:5], off
	v_lshl_add_u64 v[4:5], v[6:7], 0, 64
	v_add_u32_e32 v6, 0x6000, v142
	s_mov_b32 s10, 2
	v_readfirstlane_b32 s1, v6
	s_mov_b32 m0, s1
	v_lshl_add_u64 v[116:117], v[102:103], 0, s[12:13]
	global_load_lds_dwordx4 v[4:5], off
	v_add_u32_e32 v4, 0x7000, v142
	v_lshl_add_u64 v[118:119], v[104:105], 0, s[12:13]
	v_readfirstlane_b32 s1, v4
	v_add_u32_e32 v4, 0x8000, v142
	s_mov_b32 m0, s1
	v_readfirstlane_b32 s1, v4
	global_load_lds_dwordx4 v[0:1], off
	v_lshl_add_u64 v[0:1], v[8:9], 0, 64
	s_mov_b32 m0, s1
	v_lshl_add_u64 v[120:121], v[106:107], 0, s[6:7]
	global_load_lds_dwordx4 v[0:1], off
	v_lshl_add_u64 v[0:1], v[2:3], 0, 64
	v_add_u32_e32 v2, 0x9000, v142
	v_lshl_add_u64 v[122:123], v[108:109], 0, s[6:7]
	v_readfirstlane_b32 s1, v2
	s_mov_b32 m0, s1
	v_lshl_add_u64 v[124:125], v[110:111], 0, s[6:7]
	global_load_lds_dwordx4 v[0:1], off
	v_mov_b32_e32 v0, 0
	s_mov_b32 s1, 0
	s_mov_b64 s[6:7], 0
	v_mov_b32_e32 v1, v0
	v_mov_b32_e32 v2, v0
	v_mov_b32_e32 v3, v0
	v_mov_b32_e32 v12, v0
	v_mov_b32_e32 v13, v0
	v_mov_b32_e32 v14, v0
	v_mov_b32_e32 v15, v0
	v_mov_b32_e32 v4, v0
	v_mov_b32_e32 v5, v0
	v_mov_b32_e32 v6, v0
	v_mov_b32_e32 v7, v0
	v_mov_b32_e32 v8, v0
	v_mov_b32_e32 v9, v0
	v_mov_b32_e32 v10, v0
	v_mov_b32_e32 v11, v0
	v_mov_b32_e32 v16, v0
	v_mov_b32_e32 v17, v0
	v_mov_b32_e32 v18, v0
	v_mov_b32_e32 v19, v0
	v_mov_b32_e32 v20, v0
	v_mov_b32_e32 v21, v0
	v_mov_b32_e32 v22, v0
	v_mov_b32_e32 v23, v0
	v_mov_b32_e32 v24, v0
	v_mov_b32_e32 v25, v0
	v_mov_b32_e32 v26, v0
	v_mov_b32_e32 v27, v0
	v_mov_b32_e32 v28, v0
	v_mov_b32_e32 v29, v0
	v_mov_b32_e32 v30, v0
	v_mov_b32_e32 v31, v0
	v_mov_b32_e32 v32, v0
	v_mov_b32_e32 v33, v0
	v_mov_b32_e32 v34, v0
	v_mov_b32_e32 v35, v0
	v_mov_b32_e32 v36, v0
	v_mov_b32_e32 v37, v0
	v_mov_b32_e32 v38, v0
	v_mov_b32_e32 v39, v0
	v_mov_b32_e32 v40, v0
	v_mov_b32_e32 v41, v0
	v_mov_b32_e32 v42, v0
	v_mov_b32_e32 v43, v0
	v_mov_b32_e32 v44, v0
	v_mov_b32_e32 v45, v0
	v_mov_b32_e32 v46, v0
	v_mov_b32_e32 v47, v0
	v_mov_b32_e32 v48, v0
	v_mov_b32_e32 v49, v0
	v_mov_b32_e32 v50, v0
	v_mov_b32_e32 v51, v0
	v_mov_b32_e32 v52, v0
	v_mov_b32_e32 v53, v0
	v_mov_b32_e32 v54, v0
	v_mov_b32_e32 v55, v0
	v_mov_b32_e32 v56, v0
	v_mov_b32_e32 v57, v0
	v_mov_b32_e32 v58, v0
	v_mov_b32_e32 v59, v0
	v_mov_b32_e32 v60, v0
	v_mov_b32_e32 v61, v0
	v_mov_b32_e32 v62, v0
	v_mov_b32_e32 v63, v0
	v_mov_b32_e32 v64, v0
	v_mov_b32_e32 v65, v0
	v_mov_b32_e32 v66, v0
	v_mov_b32_e32 v67, v0
	v_mov_b32_e32 v68, v0
	v_mov_b32_e32 v69, v0
	v_mov_b32_e32 v70, v0
	v_mov_b32_e32 v71, v0
	v_mov_b32_e32 v72, v0
	v_mov_b32_e32 v73, v0
	v_mov_b32_e32 v74, v0
	v_mov_b32_e32 v75, v0
	v_mov_b32_e32 v76, v0
	v_mov_b32_e32 v77, v0
	v_mov_b32_e32 v78, v0
	v_mov_b32_e32 v79, v0
	v_mov_b32_e32 v80, v0
	v_mov_b32_e32 v81, v0
	v_mov_b32_e32 v82, v0
	v_mov_b32_e32 v83, v0
	v_mov_b32_e32 v84, v0
	v_mov_b32_e32 v85, v0
	v_mov_b32_e32 v86, v0
	v_mov_b32_e32 v87, v0
	v_mov_b32_e32 v88, v0
	v_mov_b32_e32 v89, v0
	v_mov_b32_e32 v90, v0
	v_mov_b32_e32 v91, v0
	v_mov_b32_e32 v92, v0
	v_mov_b32_e32 v93, v0
	v_mov_b32_e32 v94, v0
	v_mov_b32_e32 v95, v0
	v_readfirstlane_b32 s34, v142
	s_mov_b32 s36, 0x5000
	s_mov_b32 s37, 0xffff1000
	ds_read_b32 v252, v183
	ds_read_b32 v253, v184
	s_waitcnt lgkmcnt(0)
	v_readfirstlane_b32 s46, v252
	v_readfirstlane_b32 s47, v253
	s_barrier
	s_add_u32 s39, s34, 0xa000
	v_lshl_add_u64 v[126:127], v[124:125], 0, s[2:3]
	s_mov_b32 m0, s39
	s_nop 0
	global_load_lds_dwordx4 v[126:127], off
	v_lshl_add_u64 v[126:127], v[122:123], 0, s[2:3]
	s_add_u32 m0, s39, 0x1000
	s_nop 0
	global_load_lds_dwordx4 v[126:127], off
	v_lshl_add_u64 v[126:127], v[120:121], 0, s[2:3]
	s_add_u32 m0, s39, 0x2000
	s_nop 0
	global_load_lds_dwordx4 v[126:127], off
	v_lshl_add_u64 v[126:127], v[118:119], 0, s[2:3]
	s_add_u32 m0, s39, 0x3000
	s_nop 0
	global_load_lds_dwordx4 v[126:127], off
	v_lshl_add_u64 v[126:127], v[116:117], 0, s[2:3]
	s_add_u32 m0, s39, 0x4000
	s_nop 0
	global_load_lds_dwordx4 v[126:127], off
	s_add_u32 s39, s34, 0xf000
	v_lshl_add_u64 v[126:127], v[124:125], 0, s[30:31]
	s_mov_b32 m0, s39
	s_nop 0
	global_load_lds_dwordx4 v[126:127], off
	v_lshl_add_u64 v[126:127], v[122:123], 0, s[30:31]
	s_add_u32 m0, s39, 0x1000
	s_nop 0
	global_load_lds_dwordx4 v[126:127], off
	v_lshl_add_u64 v[126:127], v[120:121], 0, s[30:31]
	s_add_u32 m0, s39, 0x2000
	s_nop 0
	global_load_lds_dwordx4 v[126:127], off
	v_lshl_add_u64 v[126:127], v[118:119], 0, s[30:31]
	s_add_u32 m0, s39, 0x3000
	s_nop 0
	global_load_lds_dwordx4 v[126:127], off
	v_lshl_add_u64 v[126:127], v[116:117], 0, s[30:31]
	s_add_u32 m0, s39, 0x4000
	s_nop 0
	global_load_lds_dwordx4 v[126:127], off
	s_mov_b64 s[42:43], 0x100
	v_lshl_add_u64 v[124:125], v[124:125], 0, s[42:43]
	v_lshl_add_u64 v[122:123], v[122:123], 0, s[42:43]
	v_lshl_add_u64 v[120:121], v[120:121], 0, s[42:43]
	v_lshl_add_u64 v[236:237], v[118:119], 0, s[42:43]
	v_lshl_add_u64 v[126:127], v[116:117], 0, s[42:43]
	v_add_u32_e32 v170, v147, v128
	v_add_u32_e32 v172, v149, v148
	s_mov_b32 s35, 0
	s_mov_b32 s41, 14
	s_waitcnt vmcnt(15)
	s_barrier
	ds_read_b128 v[134:137], v170
	ds_read_b128 v[138:141], v170 offset:1024
	ds_read_b128 v[150:153], v170 offset:2048
	ds_read_b128 v[154:157], v170 offset:3072
	ds_read_b128 v[158:161], v170 offset:4096
	ds_read_b128 v[162:165], v170 offset:5120
	ds_read_b128 v[166:169], v172 offset:12288
	ds_read_b128 v[200:203], v172 offset:13312
	ds_read_b128 v[204:207], v172 offset:14336
	ds_read_b128 v[208:211], v172 offset:15360
.Lk_out:
	s_waitcnt lgkmcnt(0)
	v_mfma_f32_16x16x32_bf16 v[92:95], v[166:169], v[134:137], v[92:95]
	s_waitcnt vmcnt(10)
	s_barrier
	v_mfma_f32_16x16x32_bf16 v[88:91], v[200:203], v[134:137], v[88:91]
	s_cmp_eq_u32 s35, 0xf000
	s_cselect_b32 s38, s37, s36
	s_add_u32 s39, s34, s35
	v_mfma_f32_16x16x32_bf16 v[84:87], v[204:207], v[134:137], v[84:87]
	v_add_u32_e32 v170, s38, v170
	v_add_u32_e32 v172, s38, v172
	s_add_u32 s35, s35, s38
	v_mfma_f32_16x16x32_bf16 v[80:83], v[208:211], v[134:137], v[80:83]
	ds_read_b128 v[212:215], v170
	v_mfma_f32_16x16x32_bf16 v[76:79], v[166:169], v[138:141], v[76:79]
	ds_read_b128 v[216:219], v170 offset:1024
	v_mfma_f32_16x16x32_bf16 v[72:75], v[200:203], v[138:141], v[72:75]
	ds_read_b128 v[220:223], v170 offset:2048
	v_mfma_f32_16x16x32_bf16 v[68:71], v[204:207], v[138:141], v[68:71]
	ds_read_b128 v[224:227], v170 offset:3072
	v_mfma_f32_16x16x32_bf16 v[64:67], v[208:211], v[138:141], v[64:67]
	ds_read_b128 v[228:231], v170 offset:4096
	v_mfma_f32_16x16x32_bf16 v[60:63], v[166:169], v[150:153], v[60:63]
	ds_read_b128 v[232:235], v170 offset:5120
	v_mfma_f32_16x16x32_bf16 v[56:59], v[200:203], v[150:153], v[56:59]
	ds_read_b128 v[244:247], v172 offset:12288
	v_mfma_f32_16x16x32_bf16 v[52:55], v[204:207], v[150:153], v[52:55]
	ds_read_b128 v[248:251], v172 offset:13312
	v_mfma_f32_16x16x32_bf16 v[48:51], v[208:211], v[150:153], v[48:51]
	ds_read_b128 v[252:255], v172 offset:14336
	v_mfma_f32_16x16x32_bf16 v[44:47], v[166:169], v[154:157], v[44:47]
	ds_read_b128 v[116:119], v172 offset:15360
	v_mfma_f32_16x16x32_bf16 v[40:43], v[200:203], v[154:157], v[40:43]
	s_mov_b32 m0, s39
	v_mfma_f32_16x16x32_bf16 v[36:39], v[204:207], v[154:157], v[36:39]
	global_load_lds_dwordx4 v[124:125], off
	v_lshl_add_u64 v[124:125], v[124:125], 0, 64
	v_mfma_f32_16x16x32_bf16 v[32:35], v[208:211], v[154:157], v[32:35]
	s_add_u32 m0, s39, 0x1000
	v_mfma_f32_16x16x32_bf16 v[28:31], v[166:169], v[158:161], v[28:31]
	global_load_lds_dwordx4 v[122:123], off
	v_lshl_add_u64 v[122:123], v[122:123], 0, 64
	v_mfma_f32_16x16x32_bf16 v[24:27], v[200:203], v[158:161], v[24:27]
	s_add_u32 m0, s39, 0x2000
	v_mfma_f32_16x16x32_bf16 v[20:23], v[204:207], v[158:161], v[20:23]
	global_load_lds_dwordx4 v[120:121], off
	v_lshl_add_u64 v[120:121], v[120:121], 0, 64
	v_mfma_f32_16x16x32_bf16 v[16:19], v[208:211], v[158:161], v[16:19]
	s_add_u32 m0, s39, 0x3000
	v_mfma_f32_16x16x32_bf16 v[8:11], v[166:169], v[162:165], v[8:11]
	global_load_lds_dwordx4 v[236:237], off
	v_lshl_add_u64 v[236:237], v[236:237], 0, 64
	v_mfma_f32_16x16x32_bf16 v[4:7], v[200:203], v[162:165], v[4:7]
	s_add_u32 m0, s39, 0x4000
	v_mfma_f32_16x16x32_bf16 v[12:15], v[204:207], v[162:165], v[12:15]
	global_load_lds_dwordx4 v[126:127], off
	v_lshl_add_u64 v[126:127], v[126:127], 0, 64
	v_mfma_f32_16x16x32_bf16 v[0:3], v[208:211], v[162:165], v[0:3]
	s_waitcnt lgkmcnt(0)
	v_mfma_f32_16x16x32_bf16 v[92:95], v[244:247], v[212:215], v[92:95]
	s_waitcnt vmcnt(10)
	s_barrier
	v_mfma_f32_16x16x32_bf16 v[88:91], v[248:251], v[212:215], v[88:91]
	s_cmp_eq_u32 s35, 0xf000
	s_cselect_b32 s38, s37, s36
	s_add_u32 s39, s34, s35
	v_mfma_f32_16x16x32_bf16 v[84:87], v[252:255], v[212:215], v[84:87]
	v_add_u32_e32 v170, s38, v170
	v_add_u32_e32 v172, s38, v172
	s_add_u32 s35, s35, s38
	v_mfma_f32_16x16x32_bf16 v[80:83], v[116:119], v[212:215], v[80:83]
	ds_read_b128 v[134:137], v170
	v_mfma_f32_16x16x32_bf16 v[76:79], v[244:247], v[216:219], v[76:79]
	ds_read_b128 v[138:141], v170 offset:1024
	v_mfma_f32_16x16x32_bf16 v[72:75], v[248:251], v[216:219], v[72:75]
	ds_read_b128 v[150:153], v170 offset:2048
	v_mfma_f32_16x16x32_bf16 v[68:71], v[252:255], v[216:219], v[68:71]
	ds_read_b128 v[154:157], v170 offset:3072
	v_mfma_f32_16x16x32_bf16 v[64:67], v[116:119], v[216:219], v[64:67]
	ds_read_b128 v[158:161], v170 offset:4096
	v_mfma_f32_16x16x32_bf16 v[60:63], v[244:247], v[220:223], v[60:63]
	ds_read_b128 v[162:165], v170 offset:5120
	v_mfma_f32_16x16x32_bf16 v[56:59], v[248:251], v[220:223], v[56:59]
	ds_read_b128 v[166:169], v172 offset:12288
	v_mfma_f32_16x16x32_bf16 v[52:55], v[252:255], v[220:223], v[52:55]
	ds_read_b128 v[200:203], v172 offset:13312
	v_mfma_f32_16x16x32_bf16 v[48:51], v[116:119], v[220:223], v[48:51]
	ds_read_b128 v[204:207], v172 offset:14336
	v_mfma_f32_16x16x32_bf16 v[44:47], v[244:247], v[224:227], v[44:47]
	ds_read_b128 v[208:211], v172 offset:15360
	v_mfma_f32_16x16x32_bf16 v[40:43], v[248:251], v[224:227], v[40:43]
	s_mov_b32 m0, s39
	v_mfma_f32_16x16x32_bf16 v[36:39], v[252:255], v[224:227], v[36:39]
	global_load_lds_dwordx4 v[124:125], off
	v_lshl_add_u64 v[124:125], v[124:125], 0, 64
	v_mfma_f32_16x16x32_bf16 v[32:35], v[116:119], v[224:227], v[32:35]
	s_add_u32 m0, s39, 0x1000
	v_mfma_f32_16x16x32_bf16 v[28:31], v[244:247], v[228:231], v[28:31]
	global_load_lds_dwordx4 v[122:123], off
	v_lshl_add_u64 v[122:123], v[122:123], 0, 64
	v_mfma_f32_16x16x32_bf16 v[24:27], v[248:251], v[228:231], v[24:27]
	s_add_u32 m0, s39, 0x2000
	v_mfma_f32_16x16x32_bf16 v[20:23], v[252:255], v[228:231], v[20:23]
	global_load_lds_dwordx4 v[120:121], off
	v_lshl_add_u64 v[120:121], v[120:121], 0, 64
	v_mfma_f32_16x16x32_bf16 v[16:19], v[116:119], v[228:231], v[16:19]
	s_add_u32 m0, s39, 0x3000
	v_mfma_f32_16x16x32_bf16 v[8:11], v[244:247], v[232:235], v[8:11]
	global_load_lds_dwordx4 v[236:237], off
	v_lshl_add_u64 v[236:237], v[236:237], 0, 64
	v_mfma_f32_16x16x32_bf16 v[4:7], v[248:251], v[232:235], v[4:7]
	s_add_u32 m0, s39, 0x4000
	v_mfma_f32_16x16x32_bf16 v[12:15], v[252:255], v[232:235], v[12:15]
	global_load_lds_dwordx4 v[126:127], off
	v_lshl_add_u64 v[126:127], v[126:127], 0, 64
	v_mfma_f32_16x16x32_bf16 v[0:3], v[116:119], v[232:235], v[0:3]
	s_add_i32 s41, s41, -1
	s_cmp_eq_u32 s41, 0
	s_cbranch_scc0 .Lk_out
	s_waitcnt lgkmcnt(0)
	v_mfma_f32_16x16x32_bf16 v[92:95], v[166:169], v[134:137], v[92:95]
	s_waitcnt vmcnt(10)
	s_barrier
	v_mfma_f32_16x16x32_bf16 v[88:91], v[200:203], v[134:137], v[88:91]
	s_cmp_eq_u32 s35, 0xf000
	s_cselect_b32 s38, s37, s36
	v_mfma_f32_16x16x32_bf16 v[84:87], v[204:207], v[134:137], v[84:87]
	v_add_u32_e32 v170, s38, v170
	v_add_u32_e32 v172, s38, v172
	s_add_u32 s35, s35, s38
	v_mfma_f32_16x16x32_bf16 v[80:83], v[208:211], v[134:137], v[80:83]
	ds_read_b128 v[212:215], v170
	v_mfma_f32_16x16x32_bf16 v[76:79], v[166:169], v[138:141], v[76:79]
	ds_read_b128 v[216:219], v170 offset:1024
	v_mfma_f32_16x16x32_bf16 v[72:75], v[200:203], v[138:141], v[72:75]
	ds_read_b128 v[220:223], v170 offset:2048
	v_mfma_f32_16x16x32_bf16 v[68:71], v[204:207], v[138:141], v[68:71]
	ds_read_b128 v[224:227], v170 offset:3072
	v_mfma_f32_16x16x32_bf16 v[64:67], v[208:211], v[138:141], v[64:67]
	ds_read_b128 v[228:231], v170 offset:4096
	v_mfma_f32_16x16x32_bf16 v[60:63], v[166:169], v[150:153], v[60:63]
	ds_read_b128 v[232:235], v170 offset:5120
	v_mfma_f32_16x16x32_bf16 v[56:59], v[200:203], v[150:153], v[56:59]
	ds_read_b128 v[244:247], v172 offset:12288
	v_mfma_f32_16x16x32_bf16 v[52:55], v[204:207], v[150:153], v[52:55]
	ds_read_b128 v[248:251], v172 offset:13312
	v_mfma_f32_16x16x32_bf16 v[48:51], v[208:211], v[150:153], v[48:51]
	ds_read_b128 v[252:255], v172 offset:14336
	v_mfma_f32_16x16x32_bf16 v[44:47], v[166:169], v[154:157], v[44:47]
	ds_read_b128 v[116:119], v172 offset:15360
	v_mfma_f32_16x16x32_bf16 v[40:43], v[200:203], v[154:157], v[40:43]
	v_mfma_f32_16x16x32_bf16 v[36:39], v[204:207], v[154:157], v[36:39]
	v_mfma_f32_16x16x32_bf16 v[32:35], v[208:211], v[154:157], v[32:35]
	v_mfma_f32_16x16x32_bf16 v[28:31], v[166:169], v[158:161], v[28:31]
	v_mfma_f32_16x16x32_bf16 v[24:27], v[200:203], v[158:161], v[24:27]
	v_mfma_f32_16x16x32_bf16 v[20:23], v[204:207], v[158:161], v[20:23]
	v_mfma_f32_16x16x32_bf16 v[16:19], v[208:211], v[158:161], v[16:19]
	v_mfma_f32_16x16x32_bf16 v[8:11], v[166:169], v[162:165], v[8:11]
	v_mfma_f32_16x16x32_bf16 v[4:7], v[200:203], v[162:165], v[4:7]
	v_mfma_f32_16x16x32_bf16 v[12:15], v[204:207], v[162:165], v[12:15]
	v_mfma_f32_16x16x32_bf16 v[0:3], v[208:211], v[162:165], v[0:3]
	s_waitcnt lgkmcnt(0)
	v_mfma_f32_16x16x32_bf16 v[92:95], v[244:247], v[212:215], v[92:95]
	s_waitcnt vmcnt(5)
	s_barrier
	v_mfma_f32_16x16x32_bf16 v[88:91], v[248:251], v[212:215], v[88:91]
	s_cmp_eq_u32 s35, 0xf000
	s_cselect_b32 s38, s37, s36
	v_mfma_f32_16x16x32_bf16 v[84:87], v[252:255], v[212:215], v[84:87]
	v_add_u32_e32 v170, s38, v170
	v_add_u32_e32 v172, s38, v172
	s_add_u32 s35, s35, s38
	v_mfma_f32_16x16x32_bf16 v[80:83], v[116:119], v[212:215], v[80:83]
	ds_read_b128 v[134:137], v170
	v_mfma_f32_16x16x32_bf16 v[76:79], v[244:247], v[216:219], v[76:79]
	ds_read_b128 v[138:141], v170 offset:1024
	v_mfma_f32_16x16x32_bf16 v[72:75], v[248:251], v[216:219], v[72:75]
	ds_read_b128 v[150:153], v170 offset:2048
	v_mfma_f32_16x16x32_bf16 v[68:71], v[252:255], v[216:219], v[68:71]
	ds_read_b128 v[154:157], v170 offset:3072
	v_mfma_f32_16x16x32_bf16 v[64:67], v[116:119], v[216:219], v[64:67]
	ds_read_b128 v[158:161], v170 offset:4096
	v_mfma_f32_16x16x32_bf16 v[60:63], v[244:247], v[220:223], v[60:63]
	ds_read_b128 v[162:165], v170 offset:5120
	v_mfma_f32_16x16x32_bf16 v[56:59], v[248:251], v[220:223], v[56:59]
	ds_read_b128 v[166:169], v172 offset:12288
	v_mfma_f32_16x16x32_bf16 v[52:55], v[252:255], v[220:223], v[52:55]
	ds_read_b128 v[200:203], v172 offset:13312
	v_mfma_f32_16x16x32_bf16 v[48:51], v[116:119], v[220:223], v[48:51]
	ds_read_b128 v[204:207], v172 offset:14336
	v_mfma_f32_16x16x32_bf16 v[44:47], v[244:247], v[224:227], v[44:47]
	ds_read_b128 v[208:211], v172 offset:15360
	v_mfma_f32_16x16x32_bf16 v[40:43], v[248:251], v[224:227], v[40:43]
	v_mfma_f32_16x16x32_bf16 v[36:39], v[252:255], v[224:227], v[36:39]
	v_mfma_f32_16x16x32_bf16 v[32:35], v[116:119], v[224:227], v[32:35]
	v_mfma_f32_16x16x32_bf16 v[28:31], v[244:247], v[228:231], v[28:31]
	v_mfma_f32_16x16x32_bf16 v[24:27], v[248:251], v[228:231], v[24:27]
	v_mfma_f32_16x16x32_bf16 v[20:23], v[252:255], v[228:231], v[20:23]
	v_mfma_f32_16x16x32_bf16 v[16:19], v[116:119], v[228:231], v[16:19]
	v_mfma_f32_16x16x32_bf16 v[8:11], v[244:247], v[232:235], v[8:11]
	v_mfma_f32_16x16x32_bf16 v[4:7], v[248:251], v[232:235], v[4:7]
	v_mfma_f32_16x16x32_bf16 v[12:15], v[252:255], v[232:235], v[12:15]
	v_mfma_f32_16x16x32_bf16 v[0:3], v[116:119], v[232:235], v[0:3]
	s_waitcnt lgkmcnt(0)
	v_mfma_f32_16x16x32_bf16 v[92:95], v[166:169], v[134:137], v[92:95]
	s_waitcnt vmcnt(0)
	s_barrier
	v_mfma_f32_16x16x32_bf16 v[88:91], v[200:203], v[134:137], v[88:91]
	s_cmp_eq_u32 s35, 0xf000
	s_cselect_b32 s38, s37, s36
	v_mfma_f32_16x16x32_bf16 v[84:87], v[204:207], v[134:137], v[84:87]
	v_add_u32_e32 v170, s38, v170
	v_add_u32_e32 v172, s38, v172
	s_add_u32 s35, s35, s38
	v_mfma_f32_16x16x32_bf16 v[80:83], v[208:211], v[134:137], v[80:83]
	ds_read_b128 v[212:215], v170
	v_mfma_f32_16x16x32_bf16 v[76:79], v[166:169], v[138:141], v[76:79]
	ds_read_b128 v[216:219], v170 offset:1024
	v_mfma_f32_16x16x32_bf16 v[72:75], v[200:203], v[138:141], v[72:75]
	ds_read_b128 v[220:223], v170 offset:2048
	v_mfma_f32_16x16x32_bf16 v[68:71], v[204:207], v[138:141], v[68:71]
	ds_read_b128 v[224:227], v170 offset:3072
	v_mfma_f32_16x16x32_bf16 v[64:67], v[208:211], v[138:141], v[64:67]
	ds_read_b128 v[228:231], v170 offset:4096
	v_mfma_f32_16x16x32_bf16 v[60:63], v[166:169], v[150:153], v[60:63]
	ds_read_b128 v[232:235], v170 offset:5120
	v_mfma_f32_16x16x32_bf16 v[56:59], v[200:203], v[150:153], v[56:59]
	ds_read_b128 v[244:247], v172 offset:12288
	v_mfma_f32_16x16x32_bf16 v[52:55], v[204:207], v[150:153], v[52:55]
	ds_read_b128 v[248:251], v172 offset:13312
	v_mfma_f32_16x16x32_bf16 v[48:51], v[208:211], v[150:153], v[48:51]
	ds_read_b128 v[252:255], v172 offset:14336
	v_mfma_f32_16x16x32_bf16 v[44:47], v[166:169], v[154:157], v[44:47]
	ds_read_b128 v[116:119], v172 offset:15360
	v_mfma_f32_16x16x32_bf16 v[40:43], v[200:203], v[154:157], v[40:43]
	v_mfma_f32_16x16x32_bf16 v[36:39], v[204:207], v[154:157], v[36:39]
	v_mfma_f32_16x16x32_bf16 v[32:35], v[208:211], v[154:157], v[32:35]
	v_mfma_f32_16x16x32_bf16 v[28:31], v[166:169], v[158:161], v[28:31]
	v_mfma_f32_16x16x32_bf16 v[24:27], v[200:203], v[158:161], v[24:27]
	v_mfma_f32_16x16x32_bf16 v[20:23], v[204:207], v[158:161], v[20:23]
	v_mfma_f32_16x16x32_bf16 v[16:19], v[208:211], v[158:161], v[16:19]
	v_mfma_f32_16x16x32_bf16 v[8:11], v[166:169], v[162:165], v[8:11]
	v_mfma_f32_16x16x32_bf16 v[4:7], v[200:203], v[162:165], v[4:7]
	v_mfma_f32_16x16x32_bf16 v[12:15], v[204:207], v[162:165], v[12:15]
	v_mfma_f32_16x16x32_bf16 v[0:3], v[208:211], v[162:165], v[0:3]
	s_waitcnt lgkmcnt(0)
	v_mfma_f32_16x16x32_bf16 v[92:95], v[244:247], v[212:215], v[92:95]
	v_mfma_f32_16x16x32_bf16 v[88:91], v[248:251], v[212:215], v[88:91]
	v_mfma_f32_16x16x32_bf16 v[84:87], v[252:255], v[212:215], v[84:87]
	v_mfma_f32_16x16x32_bf16 v[80:83], v[116:119], v[212:215], v[80:83]
	v_mfma_f32_16x16x32_bf16 v[76:79], v[244:247], v[216:219], v[76:79]
	v_mfma_f32_16x16x32_bf16 v[72:75], v[248:251], v[216:219], v[72:75]
	v_mfma_f32_16x16x32_bf16 v[68:71], v[252:255], v[216:219], v[68:71]
	v_mfma_f32_16x16x32_bf16 v[64:67], v[116:119], v[216:219], v[64:67]
	v_mfma_f32_16x16x32_bf16 v[60:63], v[244:247], v[220:223], v[60:63]
	v_mfma_f32_16x16x32_bf16 v[56:59], v[248:251], v[220:223], v[56:59]
	v_mfma_f32_16x16x32_bf16 v[52:55], v[252:255], v[220:223], v[52:55]
	v_mfma_f32_16x16x32_bf16 v[48:51], v[116:119], v[220:223], v[48:51]
	v_mfma_f32_16x16x32_bf16 v[44:47], v[244:247], v[224:227], v[44:47]
	v_mfma_f32_16x16x32_bf16 v[40:43], v[248:251], v[224:227], v[40:43]
	v_mfma_f32_16x16x32_bf16 v[36:39], v[252:255], v[224:227], v[36:39]
	v_mfma_f32_16x16x32_bf16 v[32:35], v[116:119], v[224:227], v[32:35]
	v_mfma_f32_16x16x32_bf16 v[28:31], v[244:247], v[228:231], v[28:31]
	v_mfma_f32_16x16x32_bf16 v[24:27], v[248:251], v[228:231], v[24:27]
	v_mfma_f32_16x16x32_bf16 v[20:23], v[252:255], v[228:231], v[20:23]
	v_mfma_f32_16x16x32_bf16 v[16:19], v[116:119], v[228:231], v[16:19]
	v_mfma_f32_16x16x32_bf16 v[8:11], v[244:247], v[232:235], v[8:11]
	v_mfma_f32_16x16x32_bf16 v[4:7], v[248:251], v[232:235], v[4:7]
	v_mfma_f32_16x16x32_bf16 v[12:15], v[252:255], v[232:235], v[12:15]
	v_mfma_f32_16x16x32_bf16 v[0:3], v[116:119], v[232:235], v[0:3]
	s_barrier
	v_mov_b32_e32 v170, s46
	v_mov_b32_e32 v172, s47
	ds_write_b32 v183, v170
	ds_write_b32 v184, v172
	s_waitcnt lgkmcnt(0)
	s_add_i32 s9, s9, s51
	v_readlane_b32 s10, v241, 9
	s_cmp_eq_u32 s10, 7
	s_cbranch_scc0 .Lout_epi_ln
	v_readlane_b32 s10, v243, 21
	v_readlane_b32 s11, v243, 22
	v_readlane_b32 s12, v242, 29
	v_readlane_b32 s13, v242, 30
	v_readlane_b32 s14, v243, 11
	v_readlane_b32 s15, v243, 12
	s_mov_b32 s6, 0x3fd744fd
	v_add_u32_e32 v236, s0, v145
	v_or_b32_e32 v254, s4, v146
	v_mov_b32_e32 v255, 0
	v_or_b32_e32 v237, v236, v133
	v_lshlrev_b64 v[254:255], 2, v[254:255]
	s_nop 0
	v_lshl_add_u64 v[248:249], s[10:11], 0, v[254:255]
	v_lshl_add_u64 v[250:251], s[12:13], 0, v[254:255]
	v_lshl_add_u64 v[252:253], s[14:15], 0, v[254:255]
	s_mov_b64 s[10:11], 0x2000
	v_mov_b32_e32 v255, 0
	v_lshl_add_u64 v[252:253], v[252:253], 0, s[10:11]
	v_readlane_b32 s10, v243, 21
	v_readlane_b32 s11, v243, 22
	v_readlane_b32 s12, v243, 23
	v_readlane_b32 s13, v243, 24
	s_sub_u32 s12, s12, s10
	s_subb_u32 s13, s13, s11
	s_sub_u32 s12, s12, 0x1000000
	s_subb_u32 s13, s13, 0
	v_add_u32_e32 v254, 0, v237
	v_add_u32_e32 v236, 0xfffff000, v254
	v_cmp_lt_i32_e32 vcc, 0xfff, v254
	v_lshrrev_b32_e32 v236, 10, v236
	v_lshlrev_b32_e32 v254, 12, v254
	v_add_u32_e32 v236, 1, v236
	v_cndmask_b32_e32 v236, 0, v236, vcc
	v_lshl_add_u64 v[224:225], v[254:255], 0, v[248:249]
	v_lshl_add_u64 v[228:229], v[254:255], 0, v[250:251]
	v_add_u32_e32 v236, s8, v236
	v_mad_i64_i32 v[232:233], s[0:1], v236, s33, v[252:253]
	v_mov_b32_e32 v236, s12
	v_mov_b32_e32 v254, s13
	v_cndmask_b32_e32 v236, 0, v236, vcc
	v_cndmask_b32_e32 v254, 0, v254, vcc
	v_add_co_u32_e32 v224, vcc, v224, v236
	s_nop 0
	v_addc_co_u32_e32 v225, vcc, v225, v254, vcc
	v_add_u32_e32 v254, 16, v237
	v_add_u32_e32 v236, 0xfffff000, v254
	v_cmp_lt_i32_e32 vcc, 0xfff, v254
	v_lshrrev_b32_e32 v236, 10, v236
	v_lshlrev_b32_e32 v254, 12, v254
	v_add_u32_e32 v236, 1, v236
	v_cndmask_b32_e32 v236, 0, v236, vcc
	v_lshl_add_u64 v[226:227], v[254:255], 0, v[248:249]
	v_lshl_add_u64 v[230:231], v[254:255], 0, v[250:251]
	v_add_u32_e32 v236, s8, v236
	v_mad_i64_i32 v[234:235], s[0:1], v236, s33, v[252:253]
	v_mov_b32_e32 v236, s12
	v_mov_b32_e32 v254, s13
	v_cndmask_b32_e32 v236, 0, v236, vcc
	v_cndmask_b32_e32 v254, 0, v254, vcc
	v_add_co_u32_e32 v226, vcc, v226, v236
	s_nop 0
	v_addc_co_u32_e32 v227, vcc, v227, v254, vcc
	global_load_dwordx4 v[154:157], v[224:225], off
	global_load_dwordx4 v[116:119], v[232:233], off
	global_load_dwordx4 v[158:161], v[224:225], off offset:64
	global_load_dwordx4 v[120:123], v[232:233], off offset:64
	global_load_dwordx4 v[162:165], v[224:225], off offset:128
	global_load_dwordx4 v[124:127], v[232:233], off offset:128
	global_load_dwordx4 v[166:169], v[224:225], off offset:192
	global_load_dwordx4 v[134:137], v[232:233], off offset:192
	global_load_dwordx4 v[208:211], v[226:227], off
	global_load_dwordx4 v[138:141], v[234:235], off
	global_load_dwordx4 v[212:215], v[226:227], off offset:64
	global_load_dwordx4 v[200:203], v[234:235], off offset:64
	global_load_dwordx4 v[216:219], v[226:227], off offset:128
	global_load_dwordx4 v[204:207], v[234:235], off offset:128
	global_load_dwordx4 v[220:223], v[226:227], off offset:192
	global_load_dwordx4 v[244:247], v[234:235], off offset:192
	s_waitcnt vmcnt(0)
	v_pk_mul_f32 v[92:93], v[92:93], v[116:117]
	v_pk_mul_f32 v[94:95], v[94:95], v[118:119]
	v_pk_fma_f32 v[92:93], v[154:155], s[6:7], v[92:93] op_sel_hi:[1,0,1]
	v_pk_fma_f32 v[94:95], v[156:157], s[6:7], v[94:95] op_sel_hi:[1,0,1]
	global_store_dwordx4 v[228:229], v[92:95], off
	v_pk_mul_f32 v[88:89], v[88:89], v[120:121]
	v_pk_mul_f32 v[90:91], v[90:91], v[122:123]
	v_pk_fma_f32 v[88:89], v[158:159], s[6:7], v[88:89] op_sel_hi:[1,0,1]
	v_pk_fma_f32 v[90:91], v[160:161], s[6:7], v[90:91] op_sel_hi:[1,0,1]
	global_store_dwordx4 v[228:229], v[88:91], off offset:64
	v_pk_mul_f32 v[84:85], v[84:85], v[124:125]
	v_pk_mul_f32 v[86:87], v[86:87], v[126:127]
	v_pk_fma_f32 v[84:85], v[162:163], s[6:7], v[84:85] op_sel_hi:[1,0,1]
	v_pk_fma_f32 v[86:87], v[164:165], s[6:7], v[86:87] op_sel_hi:[1,0,1]
	global_store_dwordx4 v[228:229], v[84:87], off offset:128
	v_pk_mul_f32 v[80:81], v[80:81], v[134:135]
	v_pk_mul_f32 v[82:83], v[82:83], v[136:137]
	v_pk_fma_f32 v[80:81], v[166:167], s[6:7], v[80:81] op_sel_hi:[1,0,1]
	v_pk_fma_f32 v[82:83], v[168:169], s[6:7], v[82:83] op_sel_hi:[1,0,1]
	global_store_dwordx4 v[228:229], v[80:83], off offset:192
	v_pk_mul_f32 v[76:77], v[76:77], v[138:139]
	v_pk_mul_f32 v[78:79], v[78:79], v[140:141]
	v_pk_fma_f32 v[76:77], v[208:209], s[6:7], v[76:77] op_sel_hi:[1,0,1]
	v_pk_fma_f32 v[78:79], v[210:211], s[6:7], v[78:79] op_sel_hi:[1,0,1]
	global_store_dwordx4 v[230:231], v[76:79], off
	v_pk_mul_f32 v[72:73], v[72:73], v[200:201]
	v_pk_mul_f32 v[74:75], v[74:75], v[202:203]
	v_pk_fma_f32 v[72:73], v[212:213], s[6:7], v[72:73] op_sel_hi:[1,0,1]
	v_pk_fma_f32 v[74:75], v[214:215], s[6:7], v[74:75] op_sel_hi:[1,0,1]
	global_store_dwordx4 v[230:231], v[72:75], off offset:64
	v_pk_mul_f32 v[68:69], v[68:69], v[204:205]
	v_pk_mul_f32 v[70:71], v[70:71], v[206:207]
	v_pk_fma_f32 v[68:69], v[216:217], s[6:7], v[68:69] op_sel_hi:[1,0,1]
	v_pk_fma_f32 v[70:71], v[218:219], s[6:7], v[70:71] op_sel_hi:[1,0,1]
	global_store_dwordx4 v[230:231], v[68:71], off offset:128
	v_pk_mul_f32 v[64:65], v[64:65], v[244:245]
	v_pk_mul_f32 v[66:67], v[66:67], v[246:247]
	v_pk_fma_f32 v[64:65], v[220:221], s[6:7], v[64:65] op_sel_hi:[1,0,1]
	v_pk_fma_f32 v[66:67], v[222:223], s[6:7], v[66:67] op_sel_hi:[1,0,1]
	global_store_dwordx4 v[230:231], v[64:67], off offset:192
	v_add_u32_e32 v254, 32, v237
	v_add_u32_e32 v236, 0xfffff000, v254
	v_cmp_lt_i32_e32 vcc, 0xfff, v254
	v_lshrrev_b32_e32 v236, 10, v236
	v_lshlrev_b32_e32 v254, 12, v254
	v_add_u32_e32 v236, 1, v236
	v_cndmask_b32_e32 v236, 0, v236, vcc
	v_lshl_add_u64 v[224:225], v[254:255], 0, v[248:249]
	v_lshl_add_u64 v[228:229], v[254:255], 0, v[250:251]
	v_add_u32_e32 v236, s8, v236
	v_mad_i64_i32 v[232:233], s[0:1], v236, s33, v[252:253]
	v_mov_b32_e32 v236, s12
	v_mov_b32_e32 v254, s13
	v_cndmask_b32_e32 v236, 0, v236, vcc
	v_cndmask_b32_e32 v254, 0, v254, vcc
	v_add_co_u32_e32 v224, vcc, v224, v236
	s_nop 0
	v_addc_co_u32_e32 v225, vcc, v225, v254, vcc
	v_add_u32_e32 v254, 48, v237
	v_add_u32_e32 v236, 0xfffff000, v254
	v_cmp_lt_i32_e32 vcc, 0xfff, v254
	v_lshrrev_b32_e32 v236, 10, v236
	v_lshlrev_b32_e32 v254, 12, v254
	v_add_u32_e32 v236, 1, v236
	v_cndmask_b32_e32 v236, 0, v236, vcc
	v_lshl_add_u64 v[226:227], v[254:255], 0, v[248:249]
	v_lshl_add_u64 v[230:231], v[254:255], 0, v[250:251]
	v_add_u32_e32 v236, s8, v236
	v_mad_i64_i32 v[234:235], s[0:1], v236, s33, v[252:253]
	v_mov_b32_e32 v236, s12
	v_mov_b32_e32 v254, s13
	v_cndmask_b32_e32 v236, 0, v236, vcc
	v_cndmask_b32_e32 v254, 0, v254, vcc
	v_add_co_u32_e32 v226, vcc, v226, v236
	s_nop 0
	v_addc_co_u32_e32 v227, vcc, v227, v254, vcc
	global_load_dwordx4 v[154:157], v[224:225], off
	global_load_dwordx4 v[116:119], v[232:233], off
	global_load_dwordx4 v[158:161], v[224:225], off offset:64
	global_load_dwordx4 v[120:123], v[232:233], off offset:64
	global_load_dwordx4 v[162:165], v[224:225], off offset:128
	global_load_dwordx4 v[124:127], v[232:233], off offset:128
	global_load_dwordx4 v[166:169], v[224:225], off offset:192
	global_load_dwordx4 v[134:137], v[232:233], off offset:192
	global_load_dwordx4 v[208:211], v[226:227], off
	global_load_dwordx4 v[138:141], v[234:235], off
	global_load_dwordx4 v[212:215], v[226:227], off offset:64
	global_load_dwordx4 v[200:203], v[234:235], off offset:64
	global_load_dwordx4 v[216:219], v[226:227], off offset:128
	global_load_dwordx4 v[204:207], v[234:235], off offset:128
	global_load_dwordx4 v[220:223], v[226:227], off offset:192
	global_load_dwordx4 v[244:247], v[234:235], off offset:192
	s_waitcnt vmcnt(0)
	v_pk_mul_f32 v[60:61], v[60:61], v[116:117]
	v_pk_mul_f32 v[62:63], v[62:63], v[118:119]
	v_pk_fma_f32 v[60:61], v[154:155], s[6:7], v[60:61] op_sel_hi:[1,0,1]
	v_pk_fma_f32 v[62:63], v[156:157], s[6:7], v[62:63] op_sel_hi:[1,0,1]
	global_store_dwordx4 v[228:229], v[60:63], off
	v_pk_mul_f32 v[56:57], v[56:57], v[120:121]
	v_pk_mul_f32 v[58:59], v[58:59], v[122:123]
	v_pk_fma_f32 v[56:57], v[158:159], s[6:7], v[56:57] op_sel_hi:[1,0,1]
	v_pk_fma_f32 v[58:59], v[160:161], s[6:7], v[58:59] op_sel_hi:[1,0,1]
	global_store_dwordx4 v[228:229], v[56:59], off offset:64
	v_pk_mul_f32 v[52:53], v[52:53], v[124:125]
	v_pk_mul_f32 v[54:55], v[54:55], v[126:127]
	v_pk_fma_f32 v[52:53], v[162:163], s[6:7], v[52:53] op_sel_hi:[1,0,1]
	v_pk_fma_f32 v[54:55], v[164:165], s[6:7], v[54:55] op_sel_hi:[1,0,1]
	global_store_dwordx4 v[228:229], v[52:55], off offset:128
	v_pk_mul_f32 v[48:49], v[48:49], v[134:135]
	v_pk_mul_f32 v[50:51], v[50:51], v[136:137]
	v_pk_fma_f32 v[48:49], v[166:167], s[6:7], v[48:49] op_sel_hi:[1,0,1]
	v_pk_fma_f32 v[50:51], v[168:169], s[6:7], v[50:51] op_sel_hi:[1,0,1]
	global_store_dwordx4 v[228:229], v[48:51], off offset:192
	v_pk_mul_f32 v[44:45], v[44:45], v[138:139]
	v_pk_mul_f32 v[46:47], v[46:47], v[140:141]
	v_pk_fma_f32 v[44:45], v[208:209], s[6:7], v[44:45] op_sel_hi:[1,0,1]
	v_pk_fma_f32 v[46:47], v[210:211], s[6:7], v[46:47] op_sel_hi:[1,0,1]
	global_store_dwordx4 v[230:231], v[44:47], off
	v_pk_mul_f32 v[40:41], v[40:41], v[200:201]
	v_pk_mul_f32 v[42:43], v[42:43], v[202:203]
	v_pk_fma_f32 v[40:41], v[212:213], s[6:7], v[40:41] op_sel_hi:[1,0,1]
	v_pk_fma_f32 v[42:43], v[214:215], s[6:7], v[42:43] op_sel_hi:[1,0,1]
	global_store_dwordx4 v[230:231], v[40:43], off offset:64
	v_pk_mul_f32 v[36:37], v[36:37], v[204:205]
	v_pk_mul_f32 v[38:39], v[38:39], v[206:207]
	v_pk_fma_f32 v[36:37], v[216:217], s[6:7], v[36:37] op_sel_hi:[1,0,1]
	v_pk_fma_f32 v[38:39], v[218:219], s[6:7], v[38:39] op_sel_hi:[1,0,1]
	global_store_dwordx4 v[230:231], v[36:39], off offset:128
	v_pk_mul_f32 v[32:33], v[32:33], v[244:245]
	v_pk_mul_f32 v[34:35], v[34:35], v[246:247]
	v_pk_fma_f32 v[32:33], v[220:221], s[6:7], v[32:33] op_sel_hi:[1,0,1]
	v_pk_fma_f32 v[34:35], v[222:223], s[6:7], v[34:35] op_sel_hi:[1,0,1]
	global_store_dwordx4 v[230:231], v[32:35], off offset:192
	v_add_u32_e32 v254, 64, v237
	v_add_u32_e32 v236, 0xfffff000, v254
	v_cmp_lt_i32_e32 vcc, 0xfff, v254
	v_lshrrev_b32_e32 v236, 10, v236
	v_lshlrev_b32_e32 v254, 12, v254
	v_add_u32_e32 v236, 1, v236
	v_cndmask_b32_e32 v236, 0, v236, vcc
	v_lshl_add_u64 v[224:225], v[254:255], 0, v[248:249]
	v_lshl_add_u64 v[228:229], v[254:255], 0, v[250:251]
	v_add_u32_e32 v236, s8, v236
	v_mad_i64_i32 v[232:233], s[0:1], v236, s33, v[252:253]
	v_mov_b32_e32 v236, s12
	v_mov_b32_e32 v254, s13
	v_cndmask_b32_e32 v236, 0, v236, vcc
	v_cndmask_b32_e32 v254, 0, v254, vcc
	v_add_co_u32_e32 v224, vcc, v224, v236
	s_nop 0
	v_addc_co_u32_e32 v225, vcc, v225, v254, vcc
	v_add_u32_e32 v254, 80, v237
	v_add_u32_e32 v236, 0xfffff000, v254
	v_cmp_lt_i32_e32 vcc, 0xfff, v254
	v_lshrrev_b32_e32 v236, 10, v236
	v_lshlrev_b32_e32 v254, 12, v254
	v_add_u32_e32 v236, 1, v236
	v_cndmask_b32_e32 v236, 0, v236, vcc
	v_lshl_add_u64 v[226:227], v[254:255], 0, v[248:249]
	v_lshl_add_u64 v[230:231], v[254:255], 0, v[250:251]
	v_add_u32_e32 v236, s8, v236
	v_mad_i64_i32 v[234:235], s[0:1], v236, s33, v[252:253]
	v_mov_b32_e32 v236, s12
	v_mov_b32_e32 v254, s13
	v_cndmask_b32_e32 v236, 0, v236, vcc
	v_cndmask_b32_e32 v254, 0, v254, vcc
	v_add_co_u32_e32 v226, vcc, v226, v236
	s_nop 0
	v_addc_co_u32_e32 v227, vcc, v227, v254, vcc
	global_load_dwordx4 v[154:157], v[224:225], off
	global_load_dwordx4 v[116:119], v[232:233], off
	global_load_dwordx4 v[158:161], v[224:225], off offset:64
	global_load_dwordx4 v[120:123], v[232:233], off offset:64
	global_load_dwordx4 v[162:165], v[224:225], off offset:128
	global_load_dwordx4 v[124:127], v[232:233], off offset:128
	global_load_dwordx4 v[166:169], v[224:225], off offset:192
	global_load_dwordx4 v[134:137], v[232:233], off offset:192
	global_load_dwordx4 v[208:211], v[226:227], off
	global_load_dwordx4 v[138:141], v[234:235], off
	global_load_dwordx4 v[212:215], v[226:227], off offset:64
	global_load_dwordx4 v[200:203], v[234:235], off offset:64
	global_load_dwordx4 v[216:219], v[226:227], off offset:128
	global_load_dwordx4 v[204:207], v[234:235], off offset:128
	global_load_dwordx4 v[220:223], v[226:227], off offset:192
	global_load_dwordx4 v[244:247], v[234:235], off offset:192
	s_waitcnt vmcnt(0)
	v_pk_mul_f32 v[28:29], v[28:29], v[116:117]
	v_pk_mul_f32 v[30:31], v[30:31], v[118:119]
	v_pk_fma_f32 v[28:29], v[154:155], s[6:7], v[28:29] op_sel_hi:[1,0,1]
	v_pk_fma_f32 v[30:31], v[156:157], s[6:7], v[30:31] op_sel_hi:[1,0,1]
	global_store_dwordx4 v[228:229], v[28:31], off
	v_pk_mul_f32 v[24:25], v[24:25], v[120:121]
	v_pk_mul_f32 v[26:27], v[26:27], v[122:123]
	v_pk_fma_f32 v[24:25], v[158:159], s[6:7], v[24:25] op_sel_hi:[1,0,1]
	v_pk_fma_f32 v[26:27], v[160:161], s[6:7], v[26:27] op_sel_hi:[1,0,1]
	global_store_dwordx4 v[228:229], v[24:27], off offset:64
	v_pk_mul_f32 v[20:21], v[20:21], v[124:125]
	v_pk_mul_f32 v[22:23], v[22:23], v[126:127]
	v_pk_fma_f32 v[20:21], v[162:163], s[6:7], v[20:21] op_sel_hi:[1,0,1]
	v_pk_fma_f32 v[22:23], v[164:165], s[6:7], v[22:23] op_sel_hi:[1,0,1]
	global_store_dwordx4 v[228:229], v[20:23], off offset:128
	v_pk_mul_f32 v[16:17], v[16:17], v[134:135]
	v_pk_mul_f32 v[18:19], v[18:19], v[136:137]
	v_pk_fma_f32 v[16:17], v[166:167], s[6:7], v[16:17] op_sel_hi:[1,0,1]
	v_pk_fma_f32 v[18:19], v[168:169], s[6:7], v[18:19] op_sel_hi:[1,0,1]
	global_store_dwordx4 v[228:229], v[16:19], off offset:192
	v_pk_mul_f32 v[8:9], v[8:9], v[138:139]
	v_pk_mul_f32 v[10:11], v[10:11], v[140:141]
	v_pk_fma_f32 v[8:9], v[208:209], s[6:7], v[8:9] op_sel_hi:[1,0,1]
	v_pk_fma_f32 v[10:11], v[210:211], s[6:7], v[10:11] op_sel_hi:[1,0,1]
	global_store_dwordx4 v[230:231], v[8:11], off
	v_pk_mul_f32 v[4:5], v[4:5], v[200:201]
	v_pk_mul_f32 v[6:7], v[6:7], v[202:203]
	v_pk_fma_f32 v[4:5], v[212:213], s[6:7], v[4:5] op_sel_hi:[1,0,1]
	v_pk_fma_f32 v[6:7], v[214:215], s[6:7], v[6:7] op_sel_hi:[1,0,1]
	global_store_dwordx4 v[230:231], v[4:7], off offset:64
	v_pk_mul_f32 v[12:13], v[12:13], v[204:205]
	v_pk_mul_f32 v[14:15], v[14:15], v[206:207]
	v_pk_fma_f32 v[12:13], v[216:217], s[6:7], v[12:13] op_sel_hi:[1,0,1]
	v_pk_fma_f32 v[14:15], v[218:219], s[6:7], v[14:15] op_sel_hi:[1,0,1]
	global_store_dwordx4 v[230:231], v[12:15], off offset:128
	v_pk_mul_f32 v[0:1], v[0:1], v[244:245]
	v_pk_mul_f32 v[2:3], v[2:3], v[246:247]
	v_pk_fma_f32 v[0:1], v[220:221], s[6:7], v[0:1] op_sel_hi:[1,0,1]
	v_pk_fma_f32 v[2:3], v[222:223], s[6:7], v[2:3] op_sel_hi:[1,0,1]
	global_store_dwordx4 v[230:231], v[0:3], off offset:192
	s_branch .Lout_epi_done
.Lout_epi_ln:
	v_readlane_b32 s10, v243, 9
	v_readlane_b32 s11, v243, 10
	v_readlane_b32 s12, v242, 29
	v_readlane_b32 s13, v242, 30
	v_readlane_b32 s14, v243, 11
	v_readlane_b32 s15, v243, 12
	s_mov_b32 s6, 0x3fd744fd
	v_add_u32_e32 v236, s0, v145
	v_or_b32_e32 v254, s4, v146
	v_mov_b32_e32 v255, 0
	v_or_b32_e32 v237, v236, v133
	v_lshlrev_b64 v[254:255], 2, v[254:255]
	s_nop 0
	v_lshl_add_u64 v[250:251], s[12:13], 0, v[254:255]
	v_lshl_add_u64 v[252:253], s[14:15], 0, v[254:255]
	s_mov_b64 s[14:15], 0x2000
	v_lshl_add_u64 v[252:253], v[252:253], 0, s[14:15]
	v_readlane_b32 s12, v242, 25
	v_readlane_b32 s13, v242, 26
	v_lshl_add_u64 v[248:249], s[12:13], 0, v[254:255]
	v_readlane_b32 s12, v241, 9
	s_add_i32 s12, s12, -16
	s_mul_i32 s12, s12, 57
	s_lshr_b32 s12, s12, 9
	s_lshl_b32 s12, s12, 12
	v_readlane_b32 s14, v242, 3
	v_readlane_b32 s15, v242, 4
	s_add_u32 s14, s14, s12
	s_addc_u32 s15, s15, 0
	v_lshl_add_u64 v[224:225], s[14:15], 0, v[254:255]
	v_readlane_b32 s14, v242, 5
	v_readlane_b32 s15, v242, 6
	s_add_u32 s14, s14, s12
	s_addc_u32 s15, s15, 0
	v_lshl_add_u64 v[226:227], s[14:15], 0, v[254:255]
	global_load_dwordx4 v[96:99], v[224:225], off
	global_load_dwordx4 v[112:115], v[226:227], off
	global_load_dwordx4 v[100:103], v[224:225], off offset:64
	global_load_dwordx4 v[150:153], v[226:227], off offset:64
	global_load_dwordx4 v[104:107], v[224:225], off offset:128
	global_load_dwordx4 v[142:145], v[226:227], off offset:128
	global_load_dwordx4 v[108:111], v[224:225], off offset:192
	global_load_dwordx4 v[146:149], v[226:227], off offset:192
	v_mov_b32_e32 v255, 0
	v_add_u32_e32 v254, 0, v237
	v_add_u32_e32 v236, 0xfffff000, v254
	v_cmp_lt_i32_e32 vcc, 0xfff, v254
	v_lshrrev_b32_e32 v236, 10, v236
	v_lshlrev_b32_e32 v224, 3, v254
	v_lshlrev_b32_e32 v254, 12, v254
	v_add_u32_e32 v236, 1, v236
	v_mov_b32_e32 v225, 0
	v_cndmask_b32_e32 v236, 0, v236, vcc
	v_lshl_add_u64 v[224:225], v[224:225], 0, s[10:11]
	v_lshl_add_u64 v[228:229], v[254:255], 0, v[250:251]
	v_add_u32_e32 v236, s8, v236
	v_mad_i64_i32 v[232:233], s[0:1], v236, s33, v[252:253]
	global_load_dwordx2 v[132:133], v[224:225], off
	v_lshl_add_u64 v[224:225], v[254:255], 0, v[248:249]
	v_add_u32_e32 v254, 16, v237
	v_add_u32_e32 v236, 0xfffff000, v254
	v_cmp_lt_i32_e32 vcc, 0xfff, v254
	v_lshrrev_b32_e32 v236, 10, v236
	v_lshlrev_b32_e32 v226, 3, v254
	v_lshlrev_b32_e32 v254, 12, v254
	v_add_u32_e32 v236, 1, v236
	v_mov_b32_e32 v227, 0
	v_cndmask_b32_e32 v236, 0, v236, vcc
	v_lshl_add_u64 v[226:227], v[226:227], 0, s[10:11]
	v_lshl_add_u64 v[230:231], v[254:255], 0, v[250:251]
	v_add_u32_e32 v236, s8, v236
	v_mad_i64_i32 v[234:235], s[0:1], v236, s33, v[252:253]
	global_load_dword v128, v[226:227], off
	global_load_dword v170, v[226:227], off offset:4
	v_lshl_add_u64 v[226:227], v[254:255], 0, v[248:249]
	global_load_dwordx4 v[154:157], v[224:225], off
	global_load_dwordx4 v[116:119], v[232:233], off
	global_load_dwordx4 v[158:161], v[224:225], off offset:64
	global_load_dwordx4 v[120:123], v[232:233], off offset:64
	global_load_dwordx4 v[162:165], v[224:225], off offset:128
	global_load_dwordx4 v[124:127], v[232:233], off offset:128
	global_load_dwordx4 v[166:169], v[224:225], off offset:192
	global_load_dwordx4 v[134:137], v[232:233], off offset:192
	global_load_dwordx4 v[208:211], v[226:227], off
	global_load_dwordx4 v[138:141], v[234:235], off
	global_load_dwordx4 v[212:215], v[226:227], off offset:64
	global_load_dwordx4 v[200:203], v[234:235], off offset:64
	global_load_dwordx4 v[216:219], v[226:227], off offset:128
	global_load_dwordx4 v[204:207], v[234:235], off offset:128
	global_load_dwordx4 v[220:223], v[226:227], off offset:192
	global_load_dwordx4 v[244:247], v[234:235], off offset:192
	s_waitcnt vmcnt(0)
	v_pk_mul_f32 v[92:93], v[92:93], v[116:117]
	v_pk_add_f32 v[154:155], v[154:155], v[132:133] op_sel_hi:[1,0] neg_lo:[0,1] neg_hi:[0,1]
	v_pk_mul_f32 v[94:95], v[94:95], v[118:119]
	v_pk_add_f32 v[156:157], v[156:157], v[132:133] op_sel_hi:[1,0] neg_lo:[0,1] neg_hi:[0,1]
	v_pk_mul_f32 v[154:155], v[154:155], v[132:133] op_sel:[0,1] op_sel_hi:[1,1]
	v_pk_mul_f32 v[156:157], v[156:157], v[132:133] op_sel:[0,1] op_sel_hi:[1,1]
	v_pk_fma_f32 v[154:155], v[96:97], v[154:155], v[112:113]
	v_pk_fma_f32 v[156:157], v[98:99], v[156:157], v[114:115]
	v_pk_fma_f32 v[92:93], v[154:155], s[6:7], v[92:93] op_sel_hi:[1,0,1]
	v_pk_fma_f32 v[94:95], v[156:157], s[6:7], v[94:95] op_sel_hi:[1,0,1]
	global_store_dwordx4 v[228:229], v[92:95], off
	v_pk_mul_f32 v[88:89], v[88:89], v[120:121]
	v_pk_add_f32 v[158:159], v[158:159], v[132:133] op_sel_hi:[1,0] neg_lo:[0,1] neg_hi:[0,1]
	v_pk_mul_f32 v[90:91], v[90:91], v[122:123]
	v_pk_add_f32 v[160:161], v[160:161], v[132:133] op_sel_hi:[1,0] neg_lo:[0,1] neg_hi:[0,1]
	v_pk_mul_f32 v[158:159], v[158:159], v[132:133] op_sel:[0,1] op_sel_hi:[1,1]
	v_pk_mul_f32 v[160:161], v[160:161], v[132:133] op_sel:[0,1] op_sel_hi:[1,1]
	v_pk_fma_f32 v[158:159], v[100:101], v[158:159], v[150:151]
	v_pk_fma_f32 v[160:161], v[102:103], v[160:161], v[152:153]
	v_pk_fma_f32 v[88:89], v[158:159], s[6:7], v[88:89] op_sel_hi:[1,0,1]
	v_pk_fma_f32 v[90:91], v[160:161], s[6:7], v[90:91] op_sel_hi:[1,0,1]
	global_store_dwordx4 v[228:229], v[88:91], off offset:64
	v_pk_mul_f32 v[84:85], v[84:85], v[124:125]
	v_pk_add_f32 v[162:163], v[162:163], v[132:133] op_sel_hi:[1,0] neg_lo:[0,1] neg_hi:[0,1]
	v_pk_mul_f32 v[86:87], v[86:87], v[126:127]
	v_pk_add_f32 v[164:165], v[164:165], v[132:133] op_sel_hi:[1,0] neg_lo:[0,1] neg_hi:[0,1]
	v_pk_mul_f32 v[162:163], v[162:163], v[132:133] op_sel:[0,1] op_sel_hi:[1,1]
	v_pk_mul_f32 v[164:165], v[164:165], v[132:133] op_sel:[0,1] op_sel_hi:[1,1]
	v_pk_fma_f32 v[162:163], v[104:105], v[162:163], v[142:143]
	v_pk_fma_f32 v[164:165], v[106:107], v[164:165], v[144:145]
	v_pk_fma_f32 v[84:85], v[162:163], s[6:7], v[84:85] op_sel_hi:[1,0,1]
	v_pk_fma_f32 v[86:87], v[164:165], s[6:7], v[86:87] op_sel_hi:[1,0,1]
	global_store_dwordx4 v[228:229], v[84:87], off offset:128
	v_pk_mul_f32 v[80:81], v[80:81], v[134:135]
	v_pk_add_f32 v[166:167], v[166:167], v[132:133] op_sel_hi:[1,0] neg_lo:[0,1] neg_hi:[0,1]
	v_pk_mul_f32 v[82:83], v[82:83], v[136:137]
	v_pk_add_f32 v[168:169], v[168:169], v[132:133] op_sel_hi:[1,0] neg_lo:[0,1] neg_hi:[0,1]
	v_pk_mul_f32 v[166:167], v[166:167], v[132:133] op_sel:[0,1] op_sel_hi:[1,1]
	v_pk_mul_f32 v[168:169], v[168:169], v[132:133] op_sel:[0,1] op_sel_hi:[1,1]
	v_pk_fma_f32 v[166:167], v[108:109], v[166:167], v[146:147]
	v_pk_fma_f32 v[168:169], v[110:111], v[168:169], v[148:149]
	v_pk_fma_f32 v[80:81], v[166:167], s[6:7], v[80:81] op_sel_hi:[1,0,1]
	v_pk_fma_f32 v[82:83], v[168:169], s[6:7], v[82:83] op_sel_hi:[1,0,1]
	global_store_dwordx4 v[228:229], v[80:83], off offset:192
	v_pk_mul_f32 v[76:77], v[76:77], v[138:139]
	v_pk_add_f32 v[208:209], v[208:209], v[128:129] op_sel_hi:[1,0] neg_lo:[0,1] neg_hi:[0,1]
	v_pk_mul_f32 v[78:79], v[78:79], v[140:141]
	v_pk_add_f32 v[210:211], v[210:211], v[128:129] op_sel_hi:[1,0] neg_lo:[0,1] neg_hi:[0,1]
	v_pk_mul_f32 v[208:209], v[208:209], v[170:171] op_sel_hi:[1,0]
	v_pk_mul_f32 v[210:211], v[210:211], v[170:171] op_sel_hi:[1,0]
	v_pk_fma_f32 v[208:209], v[96:97], v[208:209], v[112:113]
	v_pk_fma_f32 v[210:211], v[98:99], v[210:211], v[114:115]
	v_pk_fma_f32 v[76:77], v[208:209], s[6:7], v[76:77] op_sel_hi:[1,0,1]
	v_pk_fma_f32 v[78:79], v[210:211], s[6:7], v[78:79] op_sel_hi:[1,0,1]
	global_store_dwordx4 v[230:231], v[76:79], off
	v_pk_mul_f32 v[72:73], v[72:73], v[200:201]
	v_pk_add_f32 v[212:213], v[212:213], v[128:129] op_sel_hi:[1,0] neg_lo:[0,1] neg_hi:[0,1]
	v_pk_mul_f32 v[74:75], v[74:75], v[202:203]
	v_pk_add_f32 v[214:215], v[214:215], v[128:129] op_sel_hi:[1,0] neg_lo:[0,1] neg_hi:[0,1]
	v_pk_mul_f32 v[212:213], v[212:213], v[170:171] op_sel_hi:[1,0]
	v_pk_mul_f32 v[214:215], v[214:215], v[170:171] op_sel_hi:[1,0]
	v_pk_fma_f32 v[212:213], v[100:101], v[212:213], v[150:151]
	v_pk_fma_f32 v[214:215], v[102:103], v[214:215], v[152:153]
	v_pk_fma_f32 v[72:73], v[212:213], s[6:7], v[72:73] op_sel_hi:[1,0,1]
	v_pk_fma_f32 v[74:75], v[214:215], s[6:7], v[74:75] op_sel_hi:[1,0,1]
	global_store_dwordx4 v[230:231], v[72:75], off offset:64
	v_pk_mul_f32 v[68:69], v[68:69], v[204:205]
	v_pk_add_f32 v[216:217], v[216:217], v[128:129] op_sel_hi:[1,0] neg_lo:[0,1] neg_hi:[0,1]
	v_pk_mul_f32 v[70:71], v[70:71], v[206:207]
	v_pk_add_f32 v[218:219], v[218:219], v[128:129] op_sel_hi:[1,0] neg_lo:[0,1] neg_hi:[0,1]
	v_pk_mul_f32 v[216:217], v[216:217], v[170:171] op_sel_hi:[1,0]
	v_pk_mul_f32 v[218:219], v[218:219], v[170:171] op_sel_hi:[1,0]
	v_pk_fma_f32 v[216:217], v[104:105], v[216:217], v[142:143]
	v_pk_fma_f32 v[218:219], v[106:107], v[218:219], v[144:145]
	v_pk_fma_f32 v[68:69], v[216:217], s[6:7], v[68:69] op_sel_hi:[1,0,1]
	v_pk_fma_f32 v[70:71], v[218:219], s[6:7], v[70:71] op_sel_hi:[1,0,1]
	global_store_dwordx4 v[230:231], v[68:71], off offset:128
	v_pk_mul_f32 v[64:65], v[64:65], v[244:245]
	v_pk_add_f32 v[220:221], v[220:221], v[128:129] op_sel_hi:[1,0] neg_lo:[0,1] neg_hi:[0,1]
	v_pk_mul_f32 v[66:67], v[66:67], v[246:247]
	v_pk_add_f32 v[222:223], v[222:223], v[128:129] op_sel_hi:[1,0] neg_lo:[0,1] neg_hi:[0,1]
	v_pk_mul_f32 v[220:221], v[220:221], v[170:171] op_sel_hi:[1,0]
	v_pk_mul_f32 v[222:223], v[222:223], v[170:171] op_sel_hi:[1,0]
	v_pk_fma_f32 v[220:221], v[108:109], v[220:221], v[146:147]
	v_pk_fma_f32 v[222:223], v[110:111], v[222:223], v[148:149]
	v_pk_fma_f32 v[64:65], v[220:221], s[6:7], v[64:65] op_sel_hi:[1,0,1]
	v_pk_fma_f32 v[66:67], v[222:223], s[6:7], v[66:67] op_sel_hi:[1,0,1]
	global_store_dwordx4 v[230:231], v[64:67], off offset:192
	v_add_u32_e32 v254, 32, v237
	v_add_u32_e32 v236, 0xfffff000, v254
	v_cmp_lt_i32_e32 vcc, 0xfff, v254
	v_lshrrev_b32_e32 v236, 10, v236
	v_lshlrev_b32_e32 v224, 3, v254
	v_lshlrev_b32_e32 v254, 12, v254
	v_add_u32_e32 v236, 1, v236
	v_mov_b32_e32 v225, 0
	v_cndmask_b32_e32 v236, 0, v236, vcc
	v_lshl_add_u64 v[224:225], v[224:225], 0, s[10:11]
	v_lshl_add_u64 v[228:229], v[254:255], 0, v[250:251]
	v_add_u32_e32 v236, s8, v236
	v_mad_i64_i32 v[232:233], s[0:1], v236, s33, v[252:253]
	global_load_dwordx2 v[132:133], v[224:225], off
	v_lshl_add_u64 v[224:225], v[254:255], 0, v[248:249]
	v_add_u32_e32 v254, 48, v237
	v_add_u32_e32 v236, 0xfffff000, v254
	v_cmp_lt_i32_e32 vcc, 0xfff, v254
	v_lshrrev_b32_e32 v236, 10, v236
	v_lshlrev_b32_e32 v226, 3, v254
	v_lshlrev_b32_e32 v254, 12, v254
	v_add_u32_e32 v236, 1, v236
	v_mov_b32_e32 v227, 0
	v_cndmask_b32_e32 v236, 0, v236, vcc
	v_lshl_add_u64 v[226:227], v[226:227], 0, s[10:11]
	v_lshl_add_u64 v[230:231], v[254:255], 0, v[250:251]
	v_add_u32_e32 v236, s8, v236
	v_mad_i64_i32 v[234:235], s[0:1], v236, s33, v[252:253]
	global_load_dword v128, v[226:227], off
	global_load_dword v170, v[226:227], off offset:4
	v_lshl_add_u64 v[226:227], v[254:255], 0, v[248:249]
	global_load_dwordx4 v[154:157], v[224:225], off
	global_load_dwordx4 v[116:119], v[232:233], off
	global_load_dwordx4 v[158:161], v[224:225], off offset:64
	global_load_dwordx4 v[120:123], v[232:233], off offset:64
	global_load_dwordx4 v[162:165], v[224:225], off offset:128
	global_load_dwordx4 v[124:127], v[232:233], off offset:128
	global_load_dwordx4 v[166:169], v[224:225], off offset:192
	global_load_dwordx4 v[134:137], v[232:233], off offset:192
	global_load_dwordx4 v[208:211], v[226:227], off
	global_load_dwordx4 v[138:141], v[234:235], off
	global_load_dwordx4 v[212:215], v[226:227], off offset:64
	global_load_dwordx4 v[200:203], v[234:235], off offset:64
	global_load_dwordx4 v[216:219], v[226:227], off offset:128
	global_load_dwordx4 v[204:207], v[234:235], off offset:128
	global_load_dwordx4 v[220:223], v[226:227], off offset:192
	global_load_dwordx4 v[244:247], v[234:235], off offset:192
	s_waitcnt vmcnt(0)
	v_pk_mul_f32 v[60:61], v[60:61], v[116:117]
	v_pk_add_f32 v[154:155], v[154:155], v[132:133] op_sel_hi:[1,0] neg_lo:[0,1] neg_hi:[0,1]
	v_pk_mul_f32 v[62:63], v[62:63], v[118:119]
	v_pk_add_f32 v[156:157], v[156:157], v[132:133] op_sel_hi:[1,0] neg_lo:[0,1] neg_hi:[0,1]
	v_pk_mul_f32 v[154:155], v[154:155], v[132:133] op_sel:[0,1] op_sel_hi:[1,1]
	v_pk_mul_f32 v[156:157], v[156:157], v[132:133] op_sel:[0,1] op_sel_hi:[1,1]
	v_pk_fma_f32 v[154:155], v[96:97], v[154:155], v[112:113]
	v_pk_fma_f32 v[156:157], v[98:99], v[156:157], v[114:115]
	v_pk_fma_f32 v[60:61], v[154:155], s[6:7], v[60:61] op_sel_hi:[1,0,1]
	v_pk_fma_f32 v[62:63], v[156:157], s[6:7], v[62:63] op_sel_hi:[1,0,1]
	global_store_dwordx4 v[228:229], v[60:63], off
	v_pk_mul_f32 v[56:57], v[56:57], v[120:121]
	v_pk_add_f32 v[158:159], v[158:159], v[132:133] op_sel_hi:[1,0] neg_lo:[0,1] neg_hi:[0,1]
	v_pk_mul_f32 v[58:59], v[58:59], v[122:123]
	v_pk_add_f32 v[160:161], v[160:161], v[132:133] op_sel_hi:[1,0] neg_lo:[0,1] neg_hi:[0,1]
	v_pk_mul_f32 v[158:159], v[158:159], v[132:133] op_sel:[0,1] op_sel_hi:[1,1]
	v_pk_mul_f32 v[160:161], v[160:161], v[132:133] op_sel:[0,1] op_sel_hi:[1,1]
	v_pk_fma_f32 v[158:159], v[100:101], v[158:159], v[150:151]
	v_pk_fma_f32 v[160:161], v[102:103], v[160:161], v[152:153]
	v_pk_fma_f32 v[56:57], v[158:159], s[6:7], v[56:57] op_sel_hi:[1,0,1]
	v_pk_fma_f32 v[58:59], v[160:161], s[6:7], v[58:59] op_sel_hi:[1,0,1]
	global_store_dwordx4 v[228:229], v[56:59], off offset:64
	v_pk_mul_f32 v[52:53], v[52:53], v[124:125]
	v_pk_add_f32 v[162:163], v[162:163], v[132:133] op_sel_hi:[1,0] neg_lo:[0,1] neg_hi:[0,1]
	v_pk_mul_f32 v[54:55], v[54:55], v[126:127]
	v_pk_add_f32 v[164:165], v[164:165], v[132:133] op_sel_hi:[1,0] neg_lo:[0,1] neg_hi:[0,1]
	v_pk_mul_f32 v[162:163], v[162:163], v[132:133] op_sel:[0,1] op_sel_hi:[1,1]
	v_pk_mul_f32 v[164:165], v[164:165], v[132:133] op_sel:[0,1] op_sel_hi:[1,1]
	v_pk_fma_f32 v[162:163], v[104:105], v[162:163], v[142:143]
	v_pk_fma_f32 v[164:165], v[106:107], v[164:165], v[144:145]
	v_pk_fma_f32 v[52:53], v[162:163], s[6:7], v[52:53] op_sel_hi:[1,0,1]
	v_pk_fma_f32 v[54:55], v[164:165], s[6:7], v[54:55] op_sel_hi:[1,0,1]
	global_store_dwordx4 v[228:229], v[52:55], off offset:128
	v_pk_mul_f32 v[48:49], v[48:49], v[134:135]
	v_pk_add_f32 v[166:167], v[166:167], v[132:133] op_sel_hi:[1,0] neg_lo:[0,1] neg_hi:[0,1]
	v_pk_mul_f32 v[50:51], v[50:51], v[136:137]
	v_pk_add_f32 v[168:169], v[168:169], v[132:133] op_sel_hi:[1,0] neg_lo:[0,1] neg_hi:[0,1]
	v_pk_mul_f32 v[166:167], v[166:167], v[132:133] op_sel:[0,1] op_sel_hi:[1,1]
	v_pk_mul_f32 v[168:169], v[168:169], v[132:133] op_sel:[0,1] op_sel_hi:[1,1]
	v_pk_fma_f32 v[166:167], v[108:109], v[166:167], v[146:147]
	v_pk_fma_f32 v[168:169], v[110:111], v[168:169], v[148:149]
	v_pk_fma_f32 v[48:49], v[166:167], s[6:7], v[48:49] op_sel_hi:[1,0,1]
	v_pk_fma_f32 v[50:51], v[168:169], s[6:7], v[50:51] op_sel_hi:[1,0,1]
	global_store_dwordx4 v[228:229], v[48:51], off offset:192
	v_pk_mul_f32 v[44:45], v[44:45], v[138:139]
	v_pk_add_f32 v[208:209], v[208:209], v[128:129] op_sel_hi:[1,0] neg_lo:[0,1] neg_hi:[0,1]
	v_pk_mul_f32 v[46:47], v[46:47], v[140:141]
	v_pk_add_f32 v[210:211], v[210:211], v[128:129] op_sel_hi:[1,0] neg_lo:[0,1] neg_hi:[0,1]
	v_pk_mul_f32 v[208:209], v[208:209], v[170:171] op_sel_hi:[1,0]
	v_pk_mul_f32 v[210:211], v[210:211], v[170:171] op_sel_hi:[1,0]
	v_pk_fma_f32 v[208:209], v[96:97], v[208:209], v[112:113]
	v_pk_fma_f32 v[210:211], v[98:99], v[210:211], v[114:115]
	v_pk_fma_f32 v[44:45], v[208:209], s[6:7], v[44:45] op_sel_hi:[1,0,1]
	v_pk_fma_f32 v[46:47], v[210:211], s[6:7], v[46:47] op_sel_hi:[1,0,1]
	global_store_dwordx4 v[230:231], v[44:47], off
	v_pk_mul_f32 v[40:41], v[40:41], v[200:201]
	v_pk_add_f32 v[212:213], v[212:213], v[128:129] op_sel_hi:[1,0] neg_lo:[0,1] neg_hi:[0,1]
	v_pk_mul_f32 v[42:43], v[42:43], v[202:203]
	v_pk_add_f32 v[214:215], v[214:215], v[128:129] op_sel_hi:[1,0] neg_lo:[0,1] neg_hi:[0,1]
	v_pk_mul_f32 v[212:213], v[212:213], v[170:171] op_sel_hi:[1,0]
	v_pk_mul_f32 v[214:215], v[214:215], v[170:171] op_sel_hi:[1,0]
	v_pk_fma_f32 v[212:213], v[100:101], v[212:213], v[150:151]
	v_pk_fma_f32 v[214:215], v[102:103], v[214:215], v[152:153]
	v_pk_fma_f32 v[40:41], v[212:213], s[6:7], v[40:41] op_sel_hi:[1,0,1]
	v_pk_fma_f32 v[42:43], v[214:215], s[6:7], v[42:43] op_sel_hi:[1,0,1]
	global_store_dwordx4 v[230:231], v[40:43], off offset:64
	v_pk_mul_f32 v[36:37], v[36:37], v[204:205]
	v_pk_add_f32 v[216:217], v[216:217], v[128:129] op_sel_hi:[1,0] neg_lo:[0,1] neg_hi:[0,1]
	v_pk_mul_f32 v[38:39], v[38:39], v[206:207]
	v_pk_add_f32 v[218:219], v[218:219], v[128:129] op_sel_hi:[1,0] neg_lo:[0,1] neg_hi:[0,1]
	v_pk_mul_f32 v[216:217], v[216:217], v[170:171] op_sel_hi:[1,0]
	v_pk_mul_f32 v[218:219], v[218:219], v[170:171] op_sel_hi:[1,0]
	v_pk_fma_f32 v[216:217], v[104:105], v[216:217], v[142:143]
	v_pk_fma_f32 v[218:219], v[106:107], v[218:219], v[144:145]
	v_pk_fma_f32 v[36:37], v[216:217], s[6:7], v[36:37] op_sel_hi:[1,0,1]
	v_pk_fma_f32 v[38:39], v[218:219], s[6:7], v[38:39] op_sel_hi:[1,0,1]
	global_store_dwordx4 v[230:231], v[36:39], off offset:128
	v_pk_mul_f32 v[32:33], v[32:33], v[244:245]
	v_pk_add_f32 v[220:221], v[220:221], v[128:129] op_sel_hi:[1,0] neg_lo:[0,1] neg_hi:[0,1]
	v_pk_mul_f32 v[34:35], v[34:35], v[246:247]
	v_pk_add_f32 v[222:223], v[222:223], v[128:129] op_sel_hi:[1,0] neg_lo:[0,1] neg_hi:[0,1]
	v_pk_mul_f32 v[220:221], v[220:221], v[170:171] op_sel_hi:[1,0]
	v_pk_mul_f32 v[222:223], v[222:223], v[170:171] op_sel_hi:[1,0]
	v_pk_fma_f32 v[220:221], v[108:109], v[220:221], v[146:147]
	v_pk_fma_f32 v[222:223], v[110:111], v[222:223], v[148:149]
	v_pk_fma_f32 v[32:33], v[220:221], s[6:7], v[32:33] op_sel_hi:[1,0,1]
	v_pk_fma_f32 v[34:35], v[222:223], s[6:7], v[34:35] op_sel_hi:[1,0,1]
	global_store_dwordx4 v[230:231], v[32:35], off offset:192
	v_add_u32_e32 v254, 64, v237
	v_add_u32_e32 v236, 0xfffff000, v254
	v_cmp_lt_i32_e32 vcc, 0xfff, v254
	v_lshrrev_b32_e32 v236, 10, v236
	v_lshlrev_b32_e32 v224, 3, v254
	v_lshlrev_b32_e32 v254, 12, v254
	v_add_u32_e32 v236, 1, v236
	v_mov_b32_e32 v225, 0
	v_cndmask_b32_e32 v236, 0, v236, vcc
	v_lshl_add_u64 v[224:225], v[224:225], 0, s[10:11]
	v_lshl_add_u64 v[228:229], v[254:255], 0, v[250:251]
	v_add_u32_e32 v236, s8, v236
	v_mad_i64_i32 v[232:233], s[0:1], v236, s33, v[252:253]
	global_load_dwordx2 v[132:133], v[224:225], off
	v_lshl_add_u64 v[224:225], v[254:255], 0, v[248:249]
	v_add_u32_e32 v254, 80, v237
	v_add_u32_e32 v236, 0xfffff000, v254
	v_cmp_lt_i32_e32 vcc, 0xfff, v254
	v_lshrrev_b32_e32 v236, 10, v236
	v_lshlrev_b32_e32 v226, 3, v254
	v_lshlrev_b32_e32 v254, 12, v254
	v_add_u32_e32 v236, 1, v236
	v_mov_b32_e32 v227, 0
	v_cndmask_b32_e32 v236, 0, v236, vcc
	v_lshl_add_u64 v[226:227], v[226:227], 0, s[10:11]
	v_lshl_add_u64 v[230:231], v[254:255], 0, v[250:251]
	v_add_u32_e32 v236, s8, v236
	v_mad_i64_i32 v[234:235], s[0:1], v236, s33, v[252:253]
	global_load_dword v128, v[226:227], off
	global_load_dword v170, v[226:227], off offset:4
	v_lshl_add_u64 v[226:227], v[254:255], 0, v[248:249]
	global_load_dwordx4 v[154:157], v[224:225], off
	global_load_dwordx4 v[116:119], v[232:233], off
	global_load_dwordx4 v[158:161], v[224:225], off offset:64
	global_load_dwordx4 v[120:123], v[232:233], off offset:64
	global_load_dwordx4 v[162:165], v[224:225], off offset:128
	global_load_dwordx4 v[124:127], v[232:233], off offset:128
	global_load_dwordx4 v[166:169], v[224:225], off offset:192
	global_load_dwordx4 v[134:137], v[232:233], off offset:192
	global_load_dwordx4 v[208:211], v[226:227], off
	global_load_dwordx4 v[138:141], v[234:235], off
	global_load_dwordx4 v[212:215], v[226:227], off offset:64
	global_load_dwordx4 v[200:203], v[234:235], off offset:64
	global_load_dwordx4 v[216:219], v[226:227], off offset:128
	global_load_dwordx4 v[204:207], v[234:235], off offset:128
	global_load_dwordx4 v[220:223], v[226:227], off offset:192
	global_load_dwordx4 v[244:247], v[234:235], off offset:192
	s_waitcnt vmcnt(0)
	v_pk_mul_f32 v[28:29], v[28:29], v[116:117]
	v_pk_add_f32 v[154:155], v[154:155], v[132:133] op_sel_hi:[1,0] neg_lo:[0,1] neg_hi:[0,1]
	v_pk_mul_f32 v[30:31], v[30:31], v[118:119]
	v_pk_add_f32 v[156:157], v[156:157], v[132:133] op_sel_hi:[1,0] neg_lo:[0,1] neg_hi:[0,1]
	v_pk_mul_f32 v[154:155], v[154:155], v[132:133] op_sel:[0,1] op_sel_hi:[1,1]
	v_pk_mul_f32 v[156:157], v[156:157], v[132:133] op_sel:[0,1] op_sel_hi:[1,1]
	v_pk_fma_f32 v[154:155], v[96:97], v[154:155], v[112:113]
	v_pk_fma_f32 v[156:157], v[98:99], v[156:157], v[114:115]
	v_pk_fma_f32 v[28:29], v[154:155], s[6:7], v[28:29] op_sel_hi:[1,0,1]
	v_pk_fma_f32 v[30:31], v[156:157], s[6:7], v[30:31] op_sel_hi:[1,0,1]
	global_store_dwordx4 v[228:229], v[28:31], off
	v_pk_mul_f32 v[24:25], v[24:25], v[120:121]
	v_pk_add_f32 v[158:159], v[158:159], v[132:133] op_sel_hi:[1,0] neg_lo:[0,1] neg_hi:[0,1]
	v_pk_mul_f32 v[26:27], v[26:27], v[122:123]
	v_pk_add_f32 v[160:161], v[160:161], v[132:133] op_sel_hi:[1,0] neg_lo:[0,1] neg_hi:[0,1]
	v_pk_mul_f32 v[158:159], v[158:159], v[132:133] op_sel:[0,1] op_sel_hi:[1,1]
	v_pk_mul_f32 v[160:161], v[160:161], v[132:133] op_sel:[0,1] op_sel_hi:[1,1]
	v_pk_fma_f32 v[158:159], v[100:101], v[158:159], v[150:151]
	v_pk_fma_f32 v[160:161], v[102:103], v[160:161], v[152:153]
	v_pk_fma_f32 v[24:25], v[158:159], s[6:7], v[24:25] op_sel_hi:[1,0,1]
	v_pk_fma_f32 v[26:27], v[160:161], s[6:7], v[26:27] op_sel_hi:[1,0,1]
	global_store_dwordx4 v[228:229], v[24:27], off offset:64
	v_pk_mul_f32 v[20:21], v[20:21], v[124:125]
	v_pk_add_f32 v[162:163], v[162:163], v[132:133] op_sel_hi:[1,0] neg_lo:[0,1] neg_hi:[0,1]
	v_pk_mul_f32 v[22:23], v[22:23], v[126:127]
	v_pk_add_f32 v[164:165], v[164:165], v[132:133] op_sel_hi:[1,0] neg_lo:[0,1] neg_hi:[0,1]
	v_pk_mul_f32 v[162:163], v[162:163], v[132:133] op_sel:[0,1] op_sel_hi:[1,1]
	v_pk_mul_f32 v[164:165], v[164:165], v[132:133] op_sel:[0,1] op_sel_hi:[1,1]
	v_pk_fma_f32 v[162:163], v[104:105], v[162:163], v[142:143]
	v_pk_fma_f32 v[164:165], v[106:107], v[164:165], v[144:145]
	v_pk_fma_f32 v[20:21], v[162:163], s[6:7], v[20:21] op_sel_hi:[1,0,1]
	v_pk_fma_f32 v[22:23], v[164:165], s[6:7], v[22:23] op_sel_hi:[1,0,1]
	global_store_dwordx4 v[228:229], v[20:23], off offset:128
	v_pk_mul_f32 v[16:17], v[16:17], v[134:135]
	v_pk_add_f32 v[166:167], v[166:167], v[132:133] op_sel_hi:[1,0] neg_lo:[0,1] neg_hi:[0,1]
	v_pk_mul_f32 v[18:19], v[18:19], v[136:137]
	v_pk_add_f32 v[168:169], v[168:169], v[132:133] op_sel_hi:[1,0] neg_lo:[0,1] neg_hi:[0,1]
	v_pk_mul_f32 v[166:167], v[166:167], v[132:133] op_sel:[0,1] op_sel_hi:[1,1]
	v_pk_mul_f32 v[168:169], v[168:169], v[132:133] op_sel:[0,1] op_sel_hi:[1,1]
	v_pk_fma_f32 v[166:167], v[108:109], v[166:167], v[146:147]
	v_pk_fma_f32 v[168:169], v[110:111], v[168:169], v[148:149]
	v_pk_fma_f32 v[16:17], v[166:167], s[6:7], v[16:17] op_sel_hi:[1,0,1]
	v_pk_fma_f32 v[18:19], v[168:169], s[6:7], v[18:19] op_sel_hi:[1,0,1]
	global_store_dwordx4 v[228:229], v[16:19], off offset:192
	v_pk_mul_f32 v[8:9], v[8:9], v[138:139]
	v_pk_add_f32 v[208:209], v[208:209], v[128:129] op_sel_hi:[1,0] neg_lo:[0,1] neg_hi:[0,1]
	v_pk_mul_f32 v[10:11], v[10:11], v[140:141]
	v_pk_add_f32 v[210:211], v[210:211], v[128:129] op_sel_hi:[1,0] neg_lo:[0,1] neg_hi:[0,1]
	v_pk_mul_f32 v[208:209], v[208:209], v[170:171] op_sel_hi:[1,0]
	v_pk_mul_f32 v[210:211], v[210:211], v[170:171] op_sel_hi:[1,0]
	v_pk_fma_f32 v[208:209], v[96:97], v[208:209], v[112:113]
	v_pk_fma_f32 v[210:211], v[98:99], v[210:211], v[114:115]
	v_pk_fma_f32 v[8:9], v[208:209], s[6:7], v[8:9] op_sel_hi:[1,0,1]
	v_pk_fma_f32 v[10:11], v[210:211], s[6:7], v[10:11] op_sel_hi:[1,0,1]
	global_store_dwordx4 v[230:231], v[8:11], off
	v_pk_mul_f32 v[4:5], v[4:5], v[200:201]
	v_pk_add_f32 v[212:213], v[212:213], v[128:129] op_sel_hi:[1,0] neg_lo:[0,1] neg_hi:[0,1]
	v_pk_mul_f32 v[6:7], v[6:7], v[202:203]
	v_pk_add_f32 v[214:215], v[214:215], v[128:129] op_sel_hi:[1,0] neg_lo:[0,1] neg_hi:[0,1]
	v_pk_mul_f32 v[212:213], v[212:213], v[170:171] op_sel_hi:[1,0]
	v_pk_mul_f32 v[214:215], v[214:215], v[170:171] op_sel_hi:[1,0]
	v_pk_fma_f32 v[212:213], v[100:101], v[212:213], v[150:151]
	v_pk_fma_f32 v[214:215], v[102:103], v[214:215], v[152:153]
	v_pk_fma_f32 v[4:5], v[212:213], s[6:7], v[4:5] op_sel_hi:[1,0,1]
	v_pk_fma_f32 v[6:7], v[214:215], s[6:7], v[6:7] op_sel_hi:[1,0,1]
	global_store_dwordx4 v[230:231], v[4:7], off offset:64
	v_pk_mul_f32 v[12:13], v[12:13], v[204:205]
	v_pk_add_f32 v[216:217], v[216:217], v[128:129] op_sel_hi:[1,0] neg_lo:[0,1] neg_hi:[0,1]
	v_pk_mul_f32 v[14:15], v[14:15], v[206:207]
	v_pk_add_f32 v[218:219], v[218:219], v[128:129] op_sel_hi:[1,0] neg_lo:[0,1] neg_hi:[0,1]
	v_pk_mul_f32 v[216:217], v[216:217], v[170:171] op_sel_hi:[1,0]
	v_pk_mul_f32 v[218:219], v[218:219], v[170:171] op_sel_hi:[1,0]
	v_pk_fma_f32 v[216:217], v[104:105], v[216:217], v[142:143]
	v_pk_fma_f32 v[218:219], v[106:107], v[218:219], v[144:145]
	v_pk_fma_f32 v[12:13], v[216:217], s[6:7], v[12:13] op_sel_hi:[1,0,1]
	v_pk_fma_f32 v[14:15], v[218:219], s[6:7], v[14:15] op_sel_hi:[1,0,1]
	global_store_dwordx4 v[230:231], v[12:15], off offset:128
	v_pk_mul_f32 v[0:1], v[0:1], v[244:245]
	v_pk_add_f32 v[220:221], v[220:221], v[128:129] op_sel_hi:[1,0] neg_lo:[0,1] neg_hi:[0,1]
	v_pk_mul_f32 v[2:3], v[2:3], v[246:247]
	v_pk_add_f32 v[222:223], v[222:223], v[128:129] op_sel_hi:[1,0] neg_lo:[0,1] neg_hi:[0,1]
	v_pk_mul_f32 v[220:221], v[220:221], v[170:171] op_sel_hi:[1,0]
	v_pk_mul_f32 v[222:223], v[222:223], v[170:171] op_sel_hi:[1,0]
	v_pk_fma_f32 v[220:221], v[108:109], v[220:221], v[146:147]
	v_pk_fma_f32 v[222:223], v[110:111], v[222:223], v[148:149]
	v_pk_fma_f32 v[0:1], v[220:221], s[6:7], v[0:1] op_sel_hi:[1,0,1]
	v_pk_fma_f32 v[2:3], v[222:223], s[6:7], v[2:3] op_sel_hi:[1,0,1]
	global_store_dwordx4 v[230:231], v[0:3], off offset:192

	.amdhsa_kernel _Z10fwd_kernel6Paramsiii
		.amdhsa_group_segment_fixed_size 81920
		.amdhsa_private_segment_fixed_size 0
		.amdhsa_kernarg_size 872
		.amdhsa_user_sgpr_count 2
		.amdhsa_user_sgpr_dispatch_ptr 0
		.amdhsa_user_sgpr_queue_ptr 0
		.amdhsa_user_sgpr_kernarg_segment_ptr 1
		.amdhsa_user_sgpr_dispatch_id 0
		.amdhsa_user_sgpr_kernarg_preload_length 0
		.amdhsa_user_sgpr_kernarg_preload_offset 0
		.amdhsa_user_sgpr_private_segment_size 0
		.amdhsa_uses_dynamic_stack 0
		.amdhsa_enable_private_segment 0
		.amdhsa_system_sgpr_workgroup_id_x 1
		.amdhsa_system_sgpr_workgroup_id_y 0
		.amdhsa_system_sgpr_workgroup_id_z 0
		.amdhsa_system_sgpr_workgroup_info 0
		.amdhsa_system_vgpr_workitem_id 2
		.amdhsa_next_free_vgpr 256
		.amdhsa_next_free_sgpr 100
		.amdhsa_accum_offset 256
		.amdhsa_reserve_vcc 1
		.amdhsa_float_round_mode_32 0
		.amdhsa_float_round_mode_16_64 0
		.amdhsa_float_denorm_mode_32 3
		.amdhsa_float_denorm_mode_16_64 3
		.amdhsa_dx10_clamp 1
		.amdhsa_ieee_mode 1
		.amdhsa_fp16_overflow 0
		.amdhsa_tg_split 0
		.amdhsa_exception_fp_ieee_invalid_op 0
		.amdhsa_exception_fp_denorm_src 0
		.amdhsa_exception_fp_ieee_div_zero 0
		.amdhsa_exception_fp_ieee_overflow 0
		.amdhsa_exception_fp_ieee_underflow 0
		.amdhsa_exception_fp_ieee_inexact 0
		.amdhsa_exception_int_div_zero 0
	.end_amdhsa_kernel

amdhsa.kernels:
  - .agpr_count:     0
    .args:
      - .offset:         0
        .size:           600
        .value_kind:     by_value
      - .offset:         600
        .size:           4
        .value_kind:     by_value
      - .offset:         604
        .size:           4
        .value_kind:     by_value
      - .offset:         608
        .size:           4
        .value_kind:     by_value
      - .offset:         616
        .size:           4
        .value_kind:     hidden_block_count_x
      - .offset:         620
        .size:           4
        .value_kind:     hidden_block_count_y
      - .offset:         624
        .size:           4
        .value_kind:     hidden_block_count_z
      - .offset:         628
        .size:           2
        .value_kind:     hidden_group_size_x
      - .offset:         630
        .size:           2
        .value_kind:     hidden_group_size_y
      - .offset:         632
        .size:           2
        .value_kind:     hidden_group_size_z
      - .offset:         634
        .size:           2
        .value_kind:     hidden_remainder_x
      - .offset:         636
        .size:           2
        .value_kind:     hidden_remainder_y
      - .offset:         638
        .size:           2
        .value_kind:     hidden_remainder_z
      - .offset:         656
        .size:           8
        .value_kind:     hidden_global_offset_x
      - .offset:         664
        .size:           8
        .value_kind:     hidden_global_offset_y
      - .offset:         672
        .size:           8
        .value_kind:     hidden_global_offset_z
      - .offset:         680
        .size:           2
        .value_kind:     hidden_grid_dims
      - .offset:         704
        .size:           8
        .value_kind:     hidden_multigrid_sync_arg
    .group_segment_fixed_size: 81920
    .kernarg_segment_align: 8
    .kernarg_segment_size: 872
    .language:       OpenCL C
    .language_version:
      - 2
      - 0
    .max_flat_workgroup_size: 256
    .name:           _Z10fwd_kernel6Paramsiii
    .private_segment_fixed_size: 0
    .sgpr_count:     106
    .sgpr_spill_count: 468
    .symbol:         _Z10fwd_kernel6Paramsiii.kd
    .uniform_work_group_size: 1
    .uses_dynamic_stack: false
    .vgpr_count:     256
    .vgpr_spill_count: 0
    .wavefront_size: 64
